# Q/K rotary epilogue (in-proj): packed f32 multiplies/adds, sign folded into the sine pair
# speedup vs baseline: 1.0078x; 1.0078x over previous
;   __device__ __forceinline__ void operator()(f32x4 (&acc)[2][2][4][2], int brow, int bcol, int wr, int wc, int fr, int fq) const {
;     ...
;     if (nt < 4) {
;       u16* dst = (u16*)(outb + (nt < 2 ? OUT_QD : OUT_KD));
;       float sc = nt < 2 ? 0.125f * 1.4426950408889634f : 1.f;
;       int cbase = (nt & 1) * 256;
;       const float2* rope = (const float2*)(p.ws + OFF_ROPE);
;       int posmask = brow < NT_P ? 4095 : 8191;
;       bool rot = (wc & 1) == 0;
;       float2 csc[4], csn[4];
; #pragma unroll
;       for (int j = 0; j < 4; ++j) csc[j] = rope[((brow + wr * 64 + fq * 4 + j) & posmask) * 8 + (fr & 7)];
; #pragma unroll
;       for (int ch = 0; ch < 8; ++ch) {
;         const int ai = ch >> 2, m = ch & 3;
;         int row0 = brow + ai * 128 + wr * 64 + m * 16 + fq * 4;
;         if (ch + 1 < 8) {
;           int rown = brow + ((ch + 1) >> 2) * 128 + wr * 64 + ((ch + 1) & 3) * 16 + fq * 4;
; #pragma unroll
;           for (int j = 0; j < 4; ++j) csn[j] = rope[((rown + j) & posmask) * 8 + (fr & 7)];
;         }
;         __builtin_amdgcn_sched_barrier(0);
;         float4 r4 = rsq[ai][m];
;         float rr[4] = {r4.x * sc, r4.y * sc, r4.z * sc, r4.w * sc};
;         float va[2][4], vb[2][4];
; #pragma unroll
;         for (int j = 0; j < 4; ++j) {
;           float2 cs = csc[j];
; #pragma unroll
;           for (int bj = 0; bj < 2; ++bj) {
;             float v = acc[ai][bj][m][0][j];
;             float pr = dpp_f<0x128>(v);
;             float sg = (fr < 8) ? -pr : pr;
;             float vr = v * cs.x + sg * cs.y;
;             v = rot ? vr : v;
;             va[bj][j] = v * rr[j];
;             vb[bj][j] = acc[ai][bj][m][1][j] * rr[j];
;           }
;         }
; #pragma unroll
;         for (int bj = 0; bj < 2; ++bj) {
;           int c = cbase + bj * 128 + wc * 32 + fr;
;           store_rm4(dst, 512, row0, c, va[bj][0], va[bj][1], va[bj][2], va[bj][3], fr & 1);
;           store_rm4(dst, 512, row0, c + 16, vb[bj][0], vb[bj][1], vb[bj][2], vb[bj][3], fr & 1);
;         }
;         __builtin_amdgcn_sched_barrier(0);
; #pragma unroll
;         for (int j = 0; j < 4; ++j) csc[j] = csn[j];
;       }
.Lmy_rope_sc_done:
	s_cmp_lt_i32 s60, 0x8000
	s_cselect_b32 s8, s97, 0x1fff
	s_add_u32 s0, s50, s4
	s_addc_u32 s1, s51, 0
	v_add_u32_e32 v186, s60, v166
	v_add_u32_e32 v186, v186, v232
	v_and_b32_e32 v188, 7, v230
	v_lshlrev_b32_e32 v188, 3, v188
	v_and_b32_e32 v217, 1, v230
	v_mov_b32_e32 v190, 0x05040100
	v_mov_b32_e32 v218, 0x03020706
	v_cmp_eq_u32_e32 vcc, 1, v217
	v_and_b32_e32 v184, 14, v230
	s_lshl_b32 s5, s60, 10
	s_add_u32 s0, s0, s5
	s_addc_u32 s1, s1, 0
	v_lshlrev_b32_e32 v184, 1, v184
	v_add_u32_e32 v217, v232, v217
	v_lshl_or_b32 v184, v217, 11, v184
	v_lshl_or_b32 v184, v166, 3, v184
	v_and_b32_e32 v217, 1, v233
	v_lshl_or_b32 v184, v217, 8, v184
	v_lshrrev_b32_e32 v217, 1, v233
	v_lshl_or_b32 v184, v217, 15, v184
	s_and_b32 s5, s47, 1
	s_lshl_b32 s5, s5, 17
	v_or_b32_e32 v184, s5, v184
	s_add_u32 s4, s0, 0x1000
	s_addc_u32 s5, s1, 0
	s_add_u32 s6, s0, 0x10000
	s_addc_u32 s7, s1, 0
	s_add_u32 s98, s4, 0x10000
	s_addc_u32 s99, s5, 0
	v_cndmask_b32_e32 v190, v190, v218, vcc
	v_cmp_gt_u32_e64 s[100:101], 8, v230
	s_bitcmp0_b32 s33, 6
	s_cbranch_scc0 .Lmy_rope_norot
	v_and_b32_e32 v217, s8, v186
	v_lshl_or_b32 v217, v217, 6, v188
	global_load_dwordx2 v[168:169], v217, s[42:43]
	v_add_u32_e32 v217, 1, v186
	v_and_b32_e32 v217, s8, v217
	v_lshl_or_b32 v217, v217, 6, v188
	global_load_dwordx2 v[170:171], v217, s[42:43]
	v_add_u32_e32 v217, 2, v186
	v_and_b32_e32 v217, s8, v217
	v_lshl_or_b32 v217, v217, 6, v188
	global_load_dwordx2 v[172:173], v217, s[42:43]
	v_add_u32_e32 v217, 3, v186
	v_and_b32_e32 v217, s8, v217
	v_lshl_or_b32 v217, v217, 6, v188
	global_load_dwordx2 v[174:175], v217, s[42:43]
	v_add_u32_e32 v217, 16, v186
	v_and_b32_e32 v217, s8, v217
	v_lshl_or_b32 v217, v217, 6, v188
	global_load_dwordx2 v[176:177], v217, s[42:43]
	v_add_u32_e32 v217, 17, v186
	v_and_b32_e32 v217, s8, v217
	v_lshl_or_b32 v217, v217, 6, v188
	global_load_dwordx2 v[178:179], v217, s[42:43]
	v_add_u32_e32 v217, 18, v186
	v_and_b32_e32 v217, s8, v217
	v_lshl_or_b32 v217, v217, 6, v188
	global_load_dwordx2 v[180:181], v217, s[42:43]
	v_add_u32_e32 v217, 19, v186
	v_and_b32_e32 v217, s8, v217
	v_lshl_or_b32 v217, v217, 6, v188
	global_load_dwordx2 v[182:183], v217, s[42:43]
	s_waitcnt vmcnt(8)
	v_pk_mul_f32 v[160:161], v[156:157], v[164:165] op_sel_hi:[1,0]
	v_pk_mul_f32 v[162:163], v[158:159], v[164:165] op_sel_hi:[1,0]
	s_waitcnt vmcnt(4)
	v_mov_b32_dpp v192, v136 row_ror:8 row_mask:0xf bank_mask:0xf bound_ctrl:1
	v_mov_b32_dpp v193, v137 row_ror:8 row_mask:0xf bank_mask:0xf bound_ctrl:1
	v_mov_b32_dpp v194, v138 row_ror:8 row_mask:0xf bank_mask:0xf bound_ctrl:1
	v_mov_b32_dpp v195, v139 row_ror:8 row_mask:0xf bank_mask:0xf bound_ctrl:1
	v_mov_b32_dpp v196, v144 row_ror:8 row_mask:0xf bank_mask:0xf bound_ctrl:1
	v_mov_b32_dpp v197, v145 row_ror:8 row_mask:0xf bank_mask:0xf bound_ctrl:1
	v_mov_b32_dpp v198, v146 row_ror:8 row_mask:0xf bank_mask:0xf bound_ctrl:1
	v_mov_b32_dpp v199, v147 row_ror:8 row_mask:0xf bank_mask:0xf bound_ctrl:1
	v_pk_mov_b32 v[208:209], v[168:169], v[170:171] op_sel:[0,0]
	v_pk_mov_b32 v[212:213], v[168:169], v[170:171] op_sel:[1,1]
	v_pk_mov_b32 v[210:211], v[172:173], v[174:175] op_sel:[0,0]
	v_pk_mov_b32 v[214:215], v[172:173], v[174:175] op_sel:[1,1]
	v_cndmask_b32_e64 v212, v212, -v212, s[100:101]
	v_cndmask_b32_e64 v213, v213, -v213, s[100:101]
	v_cndmask_b32_e64 v214, v214, -v214, s[100:101]
	v_cndmask_b32_e64 v215, v215, -v215, s[100:101]
	v_pk_mul_f32 v[192:193], v[192:193], v[212:213]
	v_pk_mul_f32 v[194:195], v[194:195], v[214:215]
	v_pk_mul_f32 v[196:197], v[196:197], v[212:213]
	v_pk_mul_f32 v[198:199], v[198:199], v[214:215]
	v_pk_mul_f32 v[136:137], v[136:137], v[208:209]
	v_pk_mul_f32 v[138:139], v[138:139], v[210:211]
	v_pk_mul_f32 v[144:145], v[144:145], v[208:209]
	v_pk_mul_f32 v[146:147], v[146:147], v[210:211]
	v_pk_add_f32 v[136:137], v[136:137], v[192:193]
	v_pk_add_f32 v[138:139], v[138:139], v[194:195]
	v_pk_add_f32 v[144:145], v[144:145], v[196:197]
	v_pk_add_f32 v[146:147], v[146:147], v[198:199]
	v_pk_mul_f32 v[136:137], v[136:137], v[160:161]
	v_pk_mul_f32 v[138:139], v[138:139], v[162:163]
	v_pk_mul_f32 v[144:145], v[144:145], v[160:161]
	v_pk_mul_f32 v[146:147], v[146:147], v[162:163]
	v_pk_mul_f32 v[140:141], v[140:141], v[160:161]
	v_pk_mul_f32 v[142:143], v[142:143], v[162:163]
	v_pk_mul_f32 v[148:149], v[148:149], v[160:161]
	v_pk_mul_f32 v[150:151], v[150:151], v[162:163]
	v_cvt_pk_bf16_f32 v200, v136, v137
	v_cvt_pk_bf16_f32 v201, v138, v139
	v_cvt_pk_bf16_f32 v202, v140, v141
	v_cvt_pk_bf16_f32 v203, v142, v143
	v_cvt_pk_bf16_f32 v204, v144, v145
	v_cvt_pk_bf16_f32 v205, v146, v147
	v_cvt_pk_bf16_f32 v206, v148, v149
	v_cvt_pk_bf16_f32 v207, v150, v151
	v_mov_b32_dpp v208, v200 quad_perm:[1,0,3,2] row_mask:0xf bank_mask:0xf bound_ctrl:1
	v_mov_b32_dpp v209, v201 quad_perm:[1,0,3,2] row_mask:0xf bank_mask:0xf bound_ctrl:1
	v_mov_b32_dpp v210, v202 quad_perm:[1,0,3,2] row_mask:0xf bank_mask:0xf bound_ctrl:1
	v_mov_b32_dpp v211, v203 quad_perm:[1,0,3,2] row_mask:0xf bank_mask:0xf bound_ctrl:1
	v_mov_b32_dpp v212, v204 quad_perm:[1,0,3,2] row_mask:0xf bank_mask:0xf bound_ctrl:1
	v_mov_b32_dpp v213, v205 quad_perm:[1,0,3,2] row_mask:0xf bank_mask:0xf bound_ctrl:1
	v_mov_b32_dpp v214, v206 quad_perm:[1,0,3,2] row_mask:0xf bank_mask:0xf bound_ctrl:1
	v_mov_b32_dpp v215, v207 quad_perm:[1,0,3,2] row_mask:0xf bank_mask:0xf bound_ctrl:1
	v_perm_b32 v200, v208, v200, v190
	v_perm_b32 v201, v209, v201, v190
	v_perm_b32 v202, v210, v202, v190
	v_perm_b32 v203, v211, v203, v190
	v_perm_b32 v204, v212, v204, v190
	v_perm_b32 v205, v213, v205, v190
	v_perm_b32 v206, v214, v206, v190
	v_perm_b32 v207, v215, v207, v190
	global_store_dword v184, v200, s[0:1]
	global_store_dword v184, v201, s[4:5]
	global_store_dword v184, v202, s[0:1] offset:128
	global_store_dword v184, v203, s[4:5] offset:128
	global_store_dword v184, v204, s[6:7]
	global_store_dword v184, v205, s[98:99]
	global_store_dword v184, v206, s[6:7] offset:128
	global_store_dword v184, v207, s[98:99] offset:128
	v_add_u32_e32 v217, 32, v186
	v_and_b32_e32 v217, s8, v217
	v_lshl_or_b32 v217, v217, 6, v188
	global_load_dwordx2 v[168:169], v217, s[42:43]
	v_add_u32_e32 v217, 33, v186
	v_and_b32_e32 v217, s8, v217
	v_lshl_or_b32 v217, v217, 6, v188
	global_load_dwordx2 v[170:171], v217, s[42:43]
	v_add_u32_e32 v217, 34, v186
	v_and_b32_e32 v217, s8, v217
	v_lshl_or_b32 v217, v217, 6, v188
	global_load_dwordx2 v[172:173], v217, s[42:43]
	v_add_u32_e32 v217, 35, v186
	v_and_b32_e32 v217, s8, v217
	v_lshl_or_b32 v217, v217, 6, v188
	global_load_dwordx2 v[174:175], v217, s[42:43]
	v_pk_mul_f32 v[160:161], v[152:153], v[164:165] op_sel_hi:[1,0]
	v_pk_mul_f32 v[162:163], v[154:155], v[164:165] op_sel_hi:[1,0]
	s_waitcnt vmcnt(12)
;   __device__ __forceinline__ void operator()(f32x4 (&acc)[2][2][4][2], int brow, int bcol, int wr, int wc, int fr, int fq) const {
;     ...
;     if (nt < 4) {
;       u16* dst = (u16*)(outb + (nt < 2 ? OUT_QD : OUT_KD));
;       float sc = nt < 2 ? 0.125f * 1.4426950408889634f : 1.f;
;       int cbase = (nt & 1) * 256;
;       const float2* rope = (const float2*)(p.ws + OFF_ROPE);
;       int posmask = brow < NT_P ? 4095 : 8191;
;       bool rot = (wc & 1) == 0;
;       float2 csc[4], csn[4];
; #pragma unroll
;       for (int j = 0; j < 4; ++j) csc[j] = rope[((brow + wr * 64 + fq * 4 + j) & posmask) * 8 + (fr & 7)];
; #pragma unroll
;       for (int ch = 0; ch < 8; ++ch) {
;         const int ai = ch >> 2, m = ch & 3;
;         int row0 = brow + ai * 128 + wr * 64 + m * 16 + fq * 4;
;         if (ch + 1 < 8) {
;           int rown = brow + ((ch + 1) >> 2) * 128 + wr * 64 + ((ch + 1) & 3) * 16 + fq * 4;
; #pragma unroll
;           for (int j = 0; j < 4; ++j) csn[j] = rope[((rown + j) & posmask) * 8 + (fr & 7)];
;         }
;         __builtin_amdgcn_sched_barrier(0);
;         float4 r4 = rsq[ai][m];
;         float rr[4] = {r4.x * sc, r4.y * sc, r4.z * sc, r4.w * sc};
;         float va[2][4], vb[2][4];
; #pragma unroll
;         for (int j = 0; j < 4; ++j) {
;           float2 cs = csc[j];
; #pragma unroll
;           for (int bj = 0; bj < 2; ++bj) {
;             float v = acc[ai][bj][m][0][j];
;             float pr = dpp_f<0x128>(v);
;             float sg = (fr < 8) ? -pr : pr;
;             float vr = v * cs.x + sg * cs.y;
;             v = rot ? vr : v;
;             va[bj][j] = v * rr[j];
;             vb[bj][j] = acc[ai][bj][m][1][j] * rr[j];
;           }
;         }
; #pragma unroll
;         for (int bj = 0; bj < 2; ++bj) {
;           int c = cbase + bj * 128 + wc * 32 + fr;
;           store_rm4(dst, 512, row0, c, va[bj][0], va[bj][1], va[bj][2], va[bj][3], fr & 1);
;           store_rm4(dst, 512, row0, c + 16, vb[bj][0], vb[bj][1], vb[bj][2], vb[bj][3], fr & 1);
;         }
;         __builtin_amdgcn_sched_barrier(0);
; #pragma unroll
;         for (int j = 0; j < 4; ++j) csc[j] = csn[j];
;       }
	v_mov_b32_dpp v192, v116 row_ror:8 row_mask:0xf bank_mask:0xf bound_ctrl:1
	v_mov_b32_dpp v193, v117 row_ror:8 row_mask:0xf bank_mask:0xf bound_ctrl:1
	v_mov_b32_dpp v194, v118 row_ror:8 row_mask:0xf bank_mask:0xf bound_ctrl:1
	v_mov_b32_dpp v195, v119 row_ror:8 row_mask:0xf bank_mask:0xf bound_ctrl:1
	v_mov_b32_dpp v196, v124 row_ror:8 row_mask:0xf bank_mask:0xf bound_ctrl:1
	v_mov_b32_dpp v197, v125 row_ror:8 row_mask:0xf bank_mask:0xf bound_ctrl:1
	v_mov_b32_dpp v198, v126 row_ror:8 row_mask:0xf bank_mask:0xf bound_ctrl:1
	v_mov_b32_dpp v199, v127 row_ror:8 row_mask:0xf bank_mask:0xf bound_ctrl:1
	v_pk_mov_b32 v[208:209], v[176:177], v[178:179] op_sel:[0,0]
	v_pk_mov_b32 v[212:213], v[176:177], v[178:179] op_sel:[1,1]
	v_pk_mov_b32 v[210:211], v[180:181], v[182:183] op_sel:[0,0]
	v_pk_mov_b32 v[214:215], v[180:181], v[182:183] op_sel:[1,1]
	v_cndmask_b32_e64 v212, v212, -v212, s[100:101]
	v_cndmask_b32_e64 v213, v213, -v213, s[100:101]
	v_cndmask_b32_e64 v214, v214, -v214, s[100:101]
	v_cndmask_b32_e64 v215, v215, -v215, s[100:101]
	v_pk_mul_f32 v[192:193], v[192:193], v[212:213]
	v_pk_mul_f32 v[194:195], v[194:195], v[214:215]
	v_pk_mul_f32 v[196:197], v[196:197], v[212:213]
	v_pk_mul_f32 v[198:199], v[198:199], v[214:215]
	v_pk_mul_f32 v[116:117], v[116:117], v[208:209]
	v_pk_mul_f32 v[118:119], v[118:119], v[210:211]
	v_pk_mul_f32 v[124:125], v[124:125], v[208:209]
	v_pk_mul_f32 v[126:127], v[126:127], v[210:211]
	v_pk_add_f32 v[116:117], v[116:117], v[192:193]
	v_pk_add_f32 v[118:119], v[118:119], v[194:195]
	v_pk_add_f32 v[124:125], v[124:125], v[196:197]
	v_pk_add_f32 v[126:127], v[126:127], v[198:199]
	v_pk_mul_f32 v[116:117], v[116:117], v[160:161]
	v_pk_mul_f32 v[118:119], v[118:119], v[162:163]
	v_pk_mul_f32 v[124:125], v[124:125], v[160:161]
	v_pk_mul_f32 v[126:127], v[126:127], v[162:163]
	v_pk_mul_f32 v[120:121], v[120:121], v[160:161]
	v_pk_mul_f32 v[122:123], v[122:123], v[162:163]
	v_pk_mul_f32 v[128:129], v[128:129], v[160:161]
	v_pk_mul_f32 v[130:131], v[130:131], v[162:163]
	v_cvt_pk_bf16_f32 v200, v116, v117
	v_cvt_pk_bf16_f32 v201, v118, v119
	v_cvt_pk_bf16_f32 v202, v120, v121
	v_cvt_pk_bf16_f32 v203, v122, v123
	v_cvt_pk_bf16_f32 v204, v124, v125
	v_cvt_pk_bf16_f32 v205, v126, v127
	v_cvt_pk_bf16_f32 v206, v128, v129
	v_cvt_pk_bf16_f32 v207, v130, v131
	v_mov_b32_dpp v208, v200 quad_perm:[1,0,3,2] row_mask:0xf bank_mask:0xf bound_ctrl:1
	v_mov_b32_dpp v209, v201 quad_perm:[1,0,3,2] row_mask:0xf bank_mask:0xf bound_ctrl:1
	v_mov_b32_dpp v210, v202 quad_perm:[1,0,3,2] row_mask:0xf bank_mask:0xf bound_ctrl:1
	v_mov_b32_dpp v211, v203 quad_perm:[1,0,3,2] row_mask:0xf bank_mask:0xf bound_ctrl:1
	v_mov_b32_dpp v212, v204 quad_perm:[1,0,3,2] row_mask:0xf bank_mask:0xf bound_ctrl:1
	v_mov_b32_dpp v213, v205 quad_perm:[1,0,3,2] row_mask:0xf bank_mask:0xf bound_ctrl:1
	v_mov_b32_dpp v214, v206 quad_perm:[1,0,3,2] row_mask:0xf bank_mask:0xf bound_ctrl:1
	v_mov_b32_dpp v215, v207 quad_perm:[1,0,3,2] row_mask:0xf bank_mask:0xf bound_ctrl:1
	v_perm_b32 v200, v208, v200, v190
	v_perm_b32 v201, v209, v201, v190
	v_perm_b32 v202, v210, v202, v190
	v_perm_b32 v203, v211, v203, v190
	v_perm_b32 v204, v212, v204, v190
	v_perm_b32 v205, v213, v205, v190
	v_perm_b32 v206, v214, v206, v190
	v_perm_b32 v207, v215, v207, v190
	global_store_dword v184, v200, s[0:1] offset:32
	global_store_dword v184, v201, s[4:5] offset:32
	global_store_dword v184, v202, s[0:1] offset:160
	global_store_dword v184, v203, s[4:5] offset:160
	global_store_dword v184, v204, s[6:7] offset:32
	global_store_dword v184, v205, s[98:99] offset:32
	global_store_dword v184, v206, s[6:7] offset:160
	global_store_dword v184, v207, s[98:99] offset:160
	v_add_u32_e32 v217, 48, v186
	v_and_b32_e32 v217, s8, v217
	v_lshl_or_b32 v217, v217, 6, v188
	global_load_dwordx2 v[176:177], v217, s[42:43]
	v_add_u32_e32 v217, 49, v186
	v_and_b32_e32 v217, s8, v217
	v_lshl_or_b32 v217, v217, 6, v188
	global_load_dwordx2 v[178:179], v217, s[42:43]
	v_add_u32_e32 v217, 50, v186
	v_and_b32_e32 v217, s8, v217
	v_lshl_or_b32 v217, v217, 6, v188
	global_load_dwordx2 v[180:181], v217, s[42:43]
	v_add_u32_e32 v217, 51, v186
	v_and_b32_e32 v217, s8, v217
	v_lshl_or_b32 v217, v217, 6, v188
	global_load_dwordx2 v[182:183], v217, s[42:43]
	v_pk_mul_f32 v[160:161], v[132:133], v[164:165] op_sel_hi:[1,0]
	v_pk_mul_f32 v[162:163], v[134:135], v[164:165] op_sel_hi:[1,0]
	s_waitcnt vmcnt(12)
;   __device__ __forceinline__ void operator()(f32x4 (&acc)[2][2][4][2], int brow, int bcol, int wr, int wc, int fr, int fq) const {
;     ...
;     if (nt < 4) {
;       u16* dst = (u16*)(outb + (nt < 2 ? OUT_QD : OUT_KD));
;       float sc = nt < 2 ? 0.125f * 1.4426950408889634f : 1.f;
;       int cbase = (nt & 1) * 256;
;       const float2* rope = (const float2*)(p.ws + OFF_ROPE);
;       int posmask = brow < NT_P ? 4095 : 8191;
;       bool rot = (wc & 1) == 0;
;       float2 csc[4], csn[4];
; #pragma unroll
;       for (int j = 0; j < 4; ++j) csc[j] = rope[((brow + wr * 64 + fq * 4 + j) & posmask) * 8 + (fr & 7)];
; #pragma unroll
;       for (int ch = 0; ch < 8; ++ch) {
;         const int ai = ch >> 2, m = ch & 3;
;         int row0 = brow + ai * 128 + wr * 64 + m * 16 + fq * 4;
;         if (ch + 1 < 8) {
;           int rown = brow + ((ch + 1) >> 2) * 128 + wr * 64 + ((ch + 1) & 3) * 16 + fq * 4;
; #pragma unroll
;           for (int j = 0; j < 4; ++j) csn[j] = rope[((rown + j) & posmask) * 8 + (fr & 7)];
;         }
;         __builtin_amdgcn_sched_barrier(0);
;         float4 r4 = rsq[ai][m];
;         float rr[4] = {r4.x * sc, r4.y * sc, r4.z * sc, r4.w * sc};
;         float va[2][4], vb[2][4];
; #pragma unroll
;         for (int j = 0; j < 4; ++j) {
;           float2 cs = csc[j];
; #pragma unroll
;           for (int bj = 0; bj < 2; ++bj) {
;             float v = acc[ai][bj][m][0][j];
;             float pr = dpp_f<0x128>(v);
;             float sg = (fr < 8) ? -pr : pr;
;             float vr = v * cs.x + sg * cs.y;
;             v = rot ? vr : v;
;             va[bj][j] = v * rr[j];
;             vb[bj][j] = acc[ai][bj][m][1][j] * rr[j];
;           }
;         }
; #pragma unroll
;         for (int bj = 0; bj < 2; ++bj) {
;           int c = cbase + bj * 128 + wc * 32 + fr;
;           store_rm4(dst, 512, row0, c, va[bj][0], va[bj][1], va[bj][2], va[bj][3], fr & 1);
;           store_rm4(dst, 512, row0, c + 16, vb[bj][0], vb[bj][1], vb[bj][2], vb[bj][3], fr & 1);
;         }
;         __builtin_amdgcn_sched_barrier(0);
; #pragma unroll
;         for (int j = 0; j < 4; ++j) csc[j] = csn[j];
;       }
	v_mov_b32_dpp v192, v96 row_ror:8 row_mask:0xf bank_mask:0xf bound_ctrl:1
	v_mov_b32_dpp v193, v97 row_ror:8 row_mask:0xf bank_mask:0xf bound_ctrl:1
	v_mov_b32_dpp v194, v98 row_ror:8 row_mask:0xf bank_mask:0xf bound_ctrl:1
	v_mov_b32_dpp v195, v99 row_ror:8 row_mask:0xf bank_mask:0xf bound_ctrl:1
	v_mov_b32_dpp v196, v104 row_ror:8 row_mask:0xf bank_mask:0xf bound_ctrl:1
	v_mov_b32_dpp v197, v105 row_ror:8 row_mask:0xf bank_mask:0xf bound_ctrl:1
	v_mov_b32_dpp v198, v106 row_ror:8 row_mask:0xf bank_mask:0xf bound_ctrl:1
	v_mov_b32_dpp v199, v107 row_ror:8 row_mask:0xf bank_mask:0xf bound_ctrl:1
	v_pk_mov_b32 v[208:209], v[168:169], v[170:171] op_sel:[0,0]
	v_pk_mov_b32 v[212:213], v[168:169], v[170:171] op_sel:[1,1]
	v_pk_mov_b32 v[210:211], v[172:173], v[174:175] op_sel:[0,0]
	v_pk_mov_b32 v[214:215], v[172:173], v[174:175] op_sel:[1,1]
	v_cndmask_b32_e64 v212, v212, -v212, s[100:101]
	v_cndmask_b32_e64 v213, v213, -v213, s[100:101]
	v_cndmask_b32_e64 v214, v214, -v214, s[100:101]
	v_cndmask_b32_e64 v215, v215, -v215, s[100:101]
	v_pk_mul_f32 v[192:193], v[192:193], v[212:213]
	v_pk_mul_f32 v[194:195], v[194:195], v[214:215]
	v_pk_mul_f32 v[196:197], v[196:197], v[212:213]
	v_pk_mul_f32 v[198:199], v[198:199], v[214:215]
	v_pk_mul_f32 v[96:97], v[96:97], v[208:209]
	v_pk_mul_f32 v[98:99], v[98:99], v[210:211]
	v_pk_mul_f32 v[104:105], v[104:105], v[208:209]
	v_pk_mul_f32 v[106:107], v[106:107], v[210:211]
	v_pk_add_f32 v[96:97], v[96:97], v[192:193]
	v_pk_add_f32 v[98:99], v[98:99], v[194:195]
	v_pk_add_f32 v[104:105], v[104:105], v[196:197]
	v_pk_add_f32 v[106:107], v[106:107], v[198:199]
	v_pk_mul_f32 v[96:97], v[96:97], v[160:161]
	v_pk_mul_f32 v[98:99], v[98:99], v[162:163]
	v_pk_mul_f32 v[104:105], v[104:105], v[160:161]
	v_pk_mul_f32 v[106:107], v[106:107], v[162:163]
	v_pk_mul_f32 v[100:101], v[100:101], v[160:161]
	v_pk_mul_f32 v[102:103], v[102:103], v[162:163]
	v_pk_mul_f32 v[108:109], v[108:109], v[160:161]
	v_pk_mul_f32 v[110:111], v[110:111], v[162:163]
	v_cvt_pk_bf16_f32 v200, v96, v97
	v_cvt_pk_bf16_f32 v201, v98, v99
	v_cvt_pk_bf16_f32 v202, v100, v101
	v_cvt_pk_bf16_f32 v203, v102, v103
	v_cvt_pk_bf16_f32 v204, v104, v105
	v_cvt_pk_bf16_f32 v205, v106, v107
	v_cvt_pk_bf16_f32 v206, v108, v109
	v_cvt_pk_bf16_f32 v207, v110, v111
	v_mov_b32_dpp v208, v200 quad_perm:[1,0,3,2] row_mask:0xf bank_mask:0xf bound_ctrl:1
	v_mov_b32_dpp v209, v201 quad_perm:[1,0,3,2] row_mask:0xf bank_mask:0xf bound_ctrl:1
	v_mov_b32_dpp v210, v202 quad_perm:[1,0,3,2] row_mask:0xf bank_mask:0xf bound_ctrl:1
	v_mov_b32_dpp v211, v203 quad_perm:[1,0,3,2] row_mask:0xf bank_mask:0xf bound_ctrl:1
	v_mov_b32_dpp v212, v204 quad_perm:[1,0,3,2] row_mask:0xf bank_mask:0xf bound_ctrl:1
	v_mov_b32_dpp v213, v205 quad_perm:[1,0,3,2] row_mask:0xf bank_mask:0xf bound_ctrl:1
	v_mov_b32_dpp v214, v206 quad_perm:[1,0,3,2] row_mask:0xf bank_mask:0xf bound_ctrl:1
	v_mov_b32_dpp v215, v207 quad_perm:[1,0,3,2] row_mask:0xf bank_mask:0xf bound_ctrl:1
	v_perm_b32 v200, v208, v200, v190
	v_perm_b32 v201, v209, v201, v190
	v_perm_b32 v202, v210, v202, v190
	v_perm_b32 v203, v211, v203, v190
	v_perm_b32 v204, v212, v204, v190
	v_perm_b32 v205, v213, v205, v190
	v_perm_b32 v206, v214, v206, v190
	v_perm_b32 v207, v215, v207, v190
	global_store_dword v184, v200, s[0:1] offset:64
	global_store_dword v184, v201, s[4:5] offset:64
	global_store_dword v184, v202, s[0:1] offset:192
	global_store_dword v184, v203, s[4:5] offset:192
	global_store_dword v184, v204, s[6:7] offset:64
	global_store_dword v184, v205, s[98:99] offset:64
	global_store_dword v184, v206, s[6:7] offset:192
	global_store_dword v184, v207, s[98:99] offset:192
	v_add_u32_e32 v217, 0x80, v186
	v_and_b32_e32 v217, s8, v217
	v_lshl_or_b32 v217, v217, 6, v188
	global_load_dwordx2 v[168:169], v217, s[42:43]
	v_add_u32_e32 v217, 0x81, v186
	v_and_b32_e32 v217, s8, v217
	v_lshl_or_b32 v217, v217, 6, v188
	global_load_dwordx2 v[170:171], v217, s[42:43]
	v_add_u32_e32 v217, 0x82, v186
	v_and_b32_e32 v217, s8, v217
	v_lshl_or_b32 v217, v217, 6, v188
	global_load_dwordx2 v[172:173], v217, s[42:43]
	v_add_u32_e32 v217, 0x83, v186
	v_and_b32_e32 v217, s8, v217
	v_lshl_or_b32 v217, v217, 6, v188
	global_load_dwordx2 v[174:175], v217, s[42:43]
	v_pk_mul_f32 v[160:161], v[112:113], v[164:165] op_sel_hi:[1,0]
	v_pk_mul_f32 v[162:163], v[114:115], v[164:165] op_sel_hi:[1,0]
	s_waitcnt vmcnt(12)
;   __device__ __forceinline__ void operator()(f32x4 (&acc)[2][2][4][2], int brow, int bcol, int wr, int wc, int fr, int fq) const {
;     ...
;     if (nt < 4) {
;       u16* dst = (u16*)(outb + (nt < 2 ? OUT_QD : OUT_KD));
;       float sc = nt < 2 ? 0.125f * 1.4426950408889634f : 1.f;
;       int cbase = (nt & 1) * 256;
;       const float2* rope = (const float2*)(p.ws + OFF_ROPE);
;       int posmask = brow < NT_P ? 4095 : 8191;
;       bool rot = (wc & 1) == 0;
;       float2 csc[4], csn[4];
; #pragma unroll
;       for (int j = 0; j < 4; ++j) csc[j] = rope[((brow + wr * 64 + fq * 4 + j) & posmask) * 8 + (fr & 7)];
; #pragma unroll
;       for (int ch = 0; ch < 8; ++ch) {
;         const int ai = ch >> 2, m = ch & 3;
;         int row0 = brow + ai * 128 + wr * 64 + m * 16 + fq * 4;
;         if (ch + 1 < 8) {
;           int rown = brow + ((ch + 1) >> 2) * 128 + wr * 64 + ((ch + 1) & 3) * 16 + fq * 4;
; #pragma unroll
;           for (int j = 0; j < 4; ++j) csn[j] = rope[((rown + j) & posmask) * 8 + (fr & 7)];
;         }
;         __builtin_amdgcn_sched_barrier(0);
;         float4 r4 = rsq[ai][m];
;         float rr[4] = {r4.x * sc, r4.y * sc, r4.z * sc, r4.w * sc};
;         float va[2][4], vb[2][4];
; #pragma unroll
;         for (int j = 0; j < 4; ++j) {
;           float2 cs = csc[j];
; #pragma unroll
;           for (int bj = 0; bj < 2; ++bj) {
;             float v = acc[ai][bj][m][0][j];
;             float pr = dpp_f<0x128>(v);
;             float sg = (fr < 8) ? -pr : pr;
;             float vr = v * cs.x + sg * cs.y;
;             v = rot ? vr : v;
;             va[bj][j] = v * rr[j];
;             vb[bj][j] = acc[ai][bj][m][1][j] * rr[j];
;           }
;         }
; #pragma unroll
;         for (int bj = 0; bj < 2; ++bj) {
;           int c = cbase + bj * 128 + wc * 32 + fr;
;           store_rm4(dst, 512, row0, c, va[bj][0], va[bj][1], va[bj][2], va[bj][3], fr & 1);
;           store_rm4(dst, 512, row0, c + 16, vb[bj][0], vb[bj][1], vb[bj][2], vb[bj][3], fr & 1);
;         }
;         __builtin_amdgcn_sched_barrier(0);
; #pragma unroll
;         for (int j = 0; j < 4; ++j) csc[j] = csn[j];
;       }
	v_mov_b32_dpp v192, v76 row_ror:8 row_mask:0xf bank_mask:0xf bound_ctrl:1
	v_mov_b32_dpp v193, v77 row_ror:8 row_mask:0xf bank_mask:0xf bound_ctrl:1
	v_mov_b32_dpp v194, v78 row_ror:8 row_mask:0xf bank_mask:0xf bound_ctrl:1
	v_mov_b32_dpp v195, v79 row_ror:8 row_mask:0xf bank_mask:0xf bound_ctrl:1
	v_mov_b32_dpp v196, v84 row_ror:8 row_mask:0xf bank_mask:0xf bound_ctrl:1
	v_mov_b32_dpp v197, v85 row_ror:8 row_mask:0xf bank_mask:0xf bound_ctrl:1
	v_mov_b32_dpp v198, v86 row_ror:8 row_mask:0xf bank_mask:0xf bound_ctrl:1
	v_mov_b32_dpp v199, v87 row_ror:8 row_mask:0xf bank_mask:0xf bound_ctrl:1
	v_pk_mov_b32 v[208:209], v[176:177], v[178:179] op_sel:[0,0]
	v_pk_mov_b32 v[212:213], v[176:177], v[178:179] op_sel:[1,1]
	v_pk_mov_b32 v[210:211], v[180:181], v[182:183] op_sel:[0,0]
	v_pk_mov_b32 v[214:215], v[180:181], v[182:183] op_sel:[1,1]
	v_cndmask_b32_e64 v212, v212, -v212, s[100:101]
	v_cndmask_b32_e64 v213, v213, -v213, s[100:101]
	v_cndmask_b32_e64 v214, v214, -v214, s[100:101]
	v_cndmask_b32_e64 v215, v215, -v215, s[100:101]
	v_pk_mul_f32 v[192:193], v[192:193], v[212:213]
	v_pk_mul_f32 v[194:195], v[194:195], v[214:215]
	v_pk_mul_f32 v[196:197], v[196:197], v[212:213]
	v_pk_mul_f32 v[198:199], v[198:199], v[214:215]
	v_pk_mul_f32 v[76:77], v[76:77], v[208:209]
	v_pk_mul_f32 v[78:79], v[78:79], v[210:211]
	v_pk_mul_f32 v[84:85], v[84:85], v[208:209]
	v_pk_mul_f32 v[86:87], v[86:87], v[210:211]
	v_pk_add_f32 v[76:77], v[76:77], v[192:193]
	v_pk_add_f32 v[78:79], v[78:79], v[194:195]
	v_pk_add_f32 v[84:85], v[84:85], v[196:197]
	v_pk_add_f32 v[86:87], v[86:87], v[198:199]
	v_pk_mul_f32 v[76:77], v[76:77], v[160:161]
	v_pk_mul_f32 v[78:79], v[78:79], v[162:163]
	v_pk_mul_f32 v[84:85], v[84:85], v[160:161]
	v_pk_mul_f32 v[86:87], v[86:87], v[162:163]
	v_pk_mul_f32 v[80:81], v[80:81], v[160:161]
	v_pk_mul_f32 v[82:83], v[82:83], v[162:163]
	v_pk_mul_f32 v[88:89], v[88:89], v[160:161]
	v_pk_mul_f32 v[90:91], v[90:91], v[162:163]
	v_cvt_pk_bf16_f32 v200, v76, v77
	v_cvt_pk_bf16_f32 v201, v78, v79
	v_cvt_pk_bf16_f32 v202, v80, v81
	v_cvt_pk_bf16_f32 v203, v82, v83
	v_cvt_pk_bf16_f32 v204, v84, v85
	v_cvt_pk_bf16_f32 v205, v86, v87
	v_cvt_pk_bf16_f32 v206, v88, v89
	v_cvt_pk_bf16_f32 v207, v90, v91
	v_mov_b32_dpp v208, v200 quad_perm:[1,0,3,2] row_mask:0xf bank_mask:0xf bound_ctrl:1
	v_mov_b32_dpp v209, v201 quad_perm:[1,0,3,2] row_mask:0xf bank_mask:0xf bound_ctrl:1
	v_mov_b32_dpp v210, v202 quad_perm:[1,0,3,2] row_mask:0xf bank_mask:0xf bound_ctrl:1
	v_mov_b32_dpp v211, v203 quad_perm:[1,0,3,2] row_mask:0xf bank_mask:0xf bound_ctrl:1
	v_mov_b32_dpp v212, v204 quad_perm:[1,0,3,2] row_mask:0xf bank_mask:0xf bound_ctrl:1
	v_mov_b32_dpp v213, v205 quad_perm:[1,0,3,2] row_mask:0xf bank_mask:0xf bound_ctrl:1
	v_mov_b32_dpp v214, v206 quad_perm:[1,0,3,2] row_mask:0xf bank_mask:0xf bound_ctrl:1
	v_mov_b32_dpp v215, v207 quad_perm:[1,0,3,2] row_mask:0xf bank_mask:0xf bound_ctrl:1
	v_perm_b32 v200, v208, v200, v190
	v_perm_b32 v201, v209, v201, v190
	v_perm_b32 v202, v210, v202, v190
	v_perm_b32 v203, v211, v203, v190
	v_perm_b32 v204, v212, v204, v190
	v_perm_b32 v205, v213, v205, v190
	v_perm_b32 v206, v214, v206, v190
	v_perm_b32 v207, v215, v207, v190
	global_store_dword v184, v200, s[0:1] offset:96
	global_store_dword v184, v201, s[4:5] offset:96
	global_store_dword v184, v202, s[0:1] offset:224
	global_store_dword v184, v203, s[4:5] offset:224
	global_store_dword v184, v204, s[6:7] offset:96
	global_store_dword v184, v205, s[98:99] offset:96
	global_store_dword v184, v206, s[6:7] offset:224
	global_store_dword v184, v207, s[98:99] offset:224
	v_add_u32_e32 v217, 0x90, v186
	v_and_b32_e32 v217, s8, v217
	v_lshl_or_b32 v217, v217, 6, v188
	global_load_dwordx2 v[176:177], v217, s[42:43]
	v_add_u32_e32 v217, 0x91, v186
	v_and_b32_e32 v217, s8, v217
	v_lshl_or_b32 v217, v217, 6, v188
	global_load_dwordx2 v[178:179], v217, s[42:43]
	v_add_u32_e32 v217, 0x92, v186
	v_and_b32_e32 v217, s8, v217
	v_lshl_or_b32 v217, v217, 6, v188
	global_load_dwordx2 v[180:181], v217, s[42:43]
	v_add_u32_e32 v217, 0x93, v186
	v_and_b32_e32 v217, s8, v217
	v_lshl_or_b32 v217, v217, 6, v188
	global_load_dwordx2 v[182:183], v217, s[42:43]
	v_pk_mul_f32 v[160:161], v[92:93], v[164:165] op_sel_hi:[1,0]
	v_pk_mul_f32 v[162:163], v[94:95], v[164:165] op_sel_hi:[1,0]
	s_waitcnt vmcnt(12)
;   __device__ __forceinline__ void operator()(f32x4 (&acc)[2][2][4][2], int brow, int bcol, int wr, int wc, int fr, int fq) const {
;     ...
;     if (nt < 4) {
;       u16* dst = (u16*)(outb + (nt < 2 ? OUT_QD : OUT_KD));
;       float sc = nt < 2 ? 0.125f * 1.4426950408889634f : 1.f;
;       int cbase = (nt & 1) * 256;
;       const float2* rope = (const float2*)(p.ws + OFF_ROPE);
;       int posmask = brow < NT_P ? 4095 : 8191;
;       bool rot = (wc & 1) == 0;
;       float2 csc[4], csn[4];
; #pragma unroll
;       for (int j = 0; j < 4; ++j) csc[j] = rope[((brow + wr * 64 + fq * 4 + j) & posmask) * 8 + (fr & 7)];
; #pragma unroll
;       for (int ch = 0; ch < 8; ++ch) {
;         const int ai = ch >> 2, m = ch & 3;
;         int row0 = brow + ai * 128 + wr * 64 + m * 16 + fq * 4;
;         if (ch + 1 < 8) {
;           int rown = brow + ((ch + 1) >> 2) * 128 + wr * 64 + ((ch + 1) & 3) * 16 + fq * 4;
; #pragma unroll
;           for (int j = 0; j < 4; ++j) csn[j] = rope[((rown + j) & posmask) * 8 + (fr & 7)];
;         }
;         __builtin_amdgcn_sched_barrier(0);
;         float4 r4 = rsq[ai][m];
;         float rr[4] = {r4.x * sc, r4.y * sc, r4.z * sc, r4.w * sc};
;         float va[2][4], vb[2][4];
; #pragma unroll
;         for (int j = 0; j < 4; ++j) {
;           float2 cs = csc[j];
; #pragma unroll
;           for (int bj = 0; bj < 2; ++bj) {
;             float v = acc[ai][bj][m][0][j];
;             float pr = dpp_f<0x128>(v);
;             float sg = (fr < 8) ? -pr : pr;
;             float vr = v * cs.x + sg * cs.y;
;             v = rot ? vr : v;
;             va[bj][j] = v * rr[j];
;             vb[bj][j] = acc[ai][bj][m][1][j] * rr[j];
;           }
;         }
; #pragma unroll
;         for (int bj = 0; bj < 2; ++bj) {
;           int c = cbase + bj * 128 + wc * 32 + fr;
;           store_rm4(dst, 512, row0, c, va[bj][0], va[bj][1], va[bj][2], va[bj][3], fr & 1);
;           store_rm4(dst, 512, row0, c + 16, vb[bj][0], vb[bj][1], vb[bj][2], vb[bj][3], fr & 1);
;         }
;         __builtin_amdgcn_sched_barrier(0);
; #pragma unroll
;         for (int j = 0; j < 4; ++j) csc[j] = csn[j];
;       }
	v_mov_b32_dpp v192, v56 row_ror:8 row_mask:0xf bank_mask:0xf bound_ctrl:1
	v_mov_b32_dpp v193, v57 row_ror:8 row_mask:0xf bank_mask:0xf bound_ctrl:1
	v_mov_b32_dpp v194, v58 row_ror:8 row_mask:0xf bank_mask:0xf bound_ctrl:1
	v_mov_b32_dpp v195, v59 row_ror:8 row_mask:0xf bank_mask:0xf bound_ctrl:1
	v_mov_b32_dpp v196, v64 row_ror:8 row_mask:0xf bank_mask:0xf bound_ctrl:1
	v_mov_b32_dpp v197, v65 row_ror:8 row_mask:0xf bank_mask:0xf bound_ctrl:1
	v_mov_b32_dpp v198, v66 row_ror:8 row_mask:0xf bank_mask:0xf bound_ctrl:1
	v_mov_b32_dpp v199, v67 row_ror:8 row_mask:0xf bank_mask:0xf bound_ctrl:1
	v_pk_mov_b32 v[208:209], v[168:169], v[170:171] op_sel:[0,0]
	v_pk_mov_b32 v[212:213], v[168:169], v[170:171] op_sel:[1,1]
	v_pk_mov_b32 v[210:211], v[172:173], v[174:175] op_sel:[0,0]
	v_pk_mov_b32 v[214:215], v[172:173], v[174:175] op_sel:[1,1]
	v_cndmask_b32_e64 v212, v212, -v212, s[100:101]
	v_cndmask_b32_e64 v213, v213, -v213, s[100:101]
	v_cndmask_b32_e64 v214, v214, -v214, s[100:101]
	v_cndmask_b32_e64 v215, v215, -v215, s[100:101]
	v_pk_mul_f32 v[192:193], v[192:193], v[212:213]
	v_pk_mul_f32 v[194:195], v[194:195], v[214:215]
	v_pk_mul_f32 v[196:197], v[196:197], v[212:213]
	v_pk_mul_f32 v[198:199], v[198:199], v[214:215]
	v_pk_mul_f32 v[56:57], v[56:57], v[208:209]
	v_pk_mul_f32 v[58:59], v[58:59], v[210:211]
	v_pk_mul_f32 v[64:65], v[64:65], v[208:209]
	v_pk_mul_f32 v[66:67], v[66:67], v[210:211]
	v_pk_add_f32 v[56:57], v[56:57], v[192:193]
	v_pk_add_f32 v[58:59], v[58:59], v[194:195]
	v_pk_add_f32 v[64:65], v[64:65], v[196:197]
	v_pk_add_f32 v[66:67], v[66:67], v[198:199]
	v_pk_mul_f32 v[56:57], v[56:57], v[160:161]
	v_pk_mul_f32 v[58:59], v[58:59], v[162:163]
	v_pk_mul_f32 v[64:65], v[64:65], v[160:161]
	v_pk_mul_f32 v[66:67], v[66:67], v[162:163]
	v_pk_mul_f32 v[60:61], v[60:61], v[160:161]
	v_pk_mul_f32 v[62:63], v[62:63], v[162:163]
	v_pk_mul_f32 v[68:69], v[68:69], v[160:161]
	v_pk_mul_f32 v[70:71], v[70:71], v[162:163]
	v_cvt_pk_bf16_f32 v200, v56, v57
	v_cvt_pk_bf16_f32 v201, v58, v59
	v_cvt_pk_bf16_f32 v202, v60, v61
	v_cvt_pk_bf16_f32 v203, v62, v63
	v_cvt_pk_bf16_f32 v204, v64, v65
	v_cvt_pk_bf16_f32 v205, v66, v67
	v_cvt_pk_bf16_f32 v206, v68, v69
	v_cvt_pk_bf16_f32 v207, v70, v71
	v_mov_b32_dpp v208, v200 quad_perm:[1,0,3,2] row_mask:0xf bank_mask:0xf bound_ctrl:1
	v_mov_b32_dpp v209, v201 quad_perm:[1,0,3,2] row_mask:0xf bank_mask:0xf bound_ctrl:1
	v_mov_b32_dpp v210, v202 quad_perm:[1,0,3,2] row_mask:0xf bank_mask:0xf bound_ctrl:1
	v_mov_b32_dpp v211, v203 quad_perm:[1,0,3,2] row_mask:0xf bank_mask:0xf bound_ctrl:1
	v_mov_b32_dpp v212, v204 quad_perm:[1,0,3,2] row_mask:0xf bank_mask:0xf bound_ctrl:1
	v_mov_b32_dpp v213, v205 quad_perm:[1,0,3,2] row_mask:0xf bank_mask:0xf bound_ctrl:1
	v_mov_b32_dpp v214, v206 quad_perm:[1,0,3,2] row_mask:0xf bank_mask:0xf bound_ctrl:1
	v_mov_b32_dpp v215, v207 quad_perm:[1,0,3,2] row_mask:0xf bank_mask:0xf bound_ctrl:1
	v_perm_b32 v200, v208, v200, v190
	v_perm_b32 v201, v209, v201, v190
	v_perm_b32 v202, v210, v202, v190
	v_perm_b32 v203, v211, v203, v190
	v_perm_b32 v204, v212, v204, v190
	v_perm_b32 v205, v213, v205, v190
	v_perm_b32 v206, v214, v206, v190
	v_perm_b32 v207, v215, v207, v190
	global_store_dword v184, v200, s[0:1] offset:1024
	global_store_dword v184, v201, s[4:5] offset:1024
	global_store_dword v184, v202, s[0:1] offset:1152
	global_store_dword v184, v203, s[4:5] offset:1152
	global_store_dword v184, v204, s[6:7] offset:1024
	global_store_dword v184, v205, s[98:99] offset:1024
	global_store_dword v184, v206, s[6:7] offset:1152
	global_store_dword v184, v207, s[98:99] offset:1152
	v_add_u32_e32 v217, 0xa0, v186
	v_and_b32_e32 v217, s8, v217
	v_lshl_or_b32 v217, v217, 6, v188
	global_load_dwordx2 v[168:169], v217, s[42:43]
	v_add_u32_e32 v217, 0xa1, v186
	v_and_b32_e32 v217, s8, v217
	v_lshl_or_b32 v217, v217, 6, v188
	global_load_dwordx2 v[170:171], v217, s[42:43]
	v_add_u32_e32 v217, 0xa2, v186
	v_and_b32_e32 v217, s8, v217
	v_lshl_or_b32 v217, v217, 6, v188
	global_load_dwordx2 v[172:173], v217, s[42:43]
	v_add_u32_e32 v217, 0xa3, v186
	v_and_b32_e32 v217, s8, v217
	v_lshl_or_b32 v217, v217, 6, v188
	global_load_dwordx2 v[174:175], v217, s[42:43]
	v_pk_mul_f32 v[160:161], v[72:73], v[164:165] op_sel_hi:[1,0]
	v_pk_mul_f32 v[162:163], v[74:75], v[164:165] op_sel_hi:[1,0]
	s_waitcnt vmcnt(12)
;   __device__ __forceinline__ void operator()(f32x4 (&acc)[2][2][4][2], int brow, int bcol, int wr, int wc, int fr, int fq) const {
;     ...
;     if (nt < 4) {
;       u16* dst = (u16*)(outb + (nt < 2 ? OUT_QD : OUT_KD));
;       float sc = nt < 2 ? 0.125f * 1.4426950408889634f : 1.f;
;       int cbase = (nt & 1) * 256;
;       const float2* rope = (const float2*)(p.ws + OFF_ROPE);
;       int posmask = brow < NT_P ? 4095 : 8191;
;       bool rot = (wc & 1) == 0;
;       float2 csc[4], csn[4];
; #pragma unroll
;       for (int j = 0; j < 4; ++j) csc[j] = rope[((brow + wr * 64 + fq * 4 + j) & posmask) * 8 + (fr & 7)];
; #pragma unroll
;       for (int ch = 0; ch < 8; ++ch) {
;         const int ai = ch >> 2, m = ch & 3;
;         int row0 = brow + ai * 128 + wr * 64 + m * 16 + fq * 4;
;         if (ch + 1 < 8) {
;           int rown = brow + ((ch + 1) >> 2) * 128 + wr * 64 + ((ch + 1) & 3) * 16 + fq * 4;
; #pragma unroll
;           for (int j = 0; j < 4; ++j) csn[j] = rope[((rown + j) & posmask) * 8 + (fr & 7)];
;         }
;         __builtin_amdgcn_sched_barrier(0);
;         float4 r4 = rsq[ai][m];
;         float rr[4] = {r4.x * sc, r4.y * sc, r4.z * sc, r4.w * sc};
;         float va[2][4], vb[2][4];
; #pragma unroll
;         for (int j = 0; j < 4; ++j) {
;           float2 cs = csc[j];
; #pragma unroll
;           for (int bj = 0; bj < 2; ++bj) {
;             float v = acc[ai][bj][m][0][j];
;             float pr = dpp_f<0x128>(v);
;             float sg = (fr < 8) ? -pr : pr;
;             float vr = v * cs.x + sg * cs.y;
;             v = rot ? vr : v;
;             va[bj][j] = v * rr[j];
;             vb[bj][j] = acc[ai][bj][m][1][j] * rr[j];
;           }
;         }
; #pragma unroll
;         for (int bj = 0; bj < 2; ++bj) {
;           int c = cbase + bj * 128 + wc * 32 + fr;
;           store_rm4(dst, 512, row0, c, va[bj][0], va[bj][1], va[bj][2], va[bj][3], fr & 1);
;           store_rm4(dst, 512, row0, c + 16, vb[bj][0], vb[bj][1], vb[bj][2], vb[bj][3], fr & 1);
;         }
;         __builtin_amdgcn_sched_barrier(0);
; #pragma unroll
;         for (int j = 0; j < 4; ++j) csc[j] = csn[j];
;       }
	v_mov_b32_dpp v192, v36 row_ror:8 row_mask:0xf bank_mask:0xf bound_ctrl:1
	v_mov_b32_dpp v193, v37 row_ror:8 row_mask:0xf bank_mask:0xf bound_ctrl:1
	v_mov_b32_dpp v194, v38 row_ror:8 row_mask:0xf bank_mask:0xf bound_ctrl:1
	v_mov_b32_dpp v195, v39 row_ror:8 row_mask:0xf bank_mask:0xf bound_ctrl:1
	v_mov_b32_dpp v196, v44 row_ror:8 row_mask:0xf bank_mask:0xf bound_ctrl:1
	v_mov_b32_dpp v197, v45 row_ror:8 row_mask:0xf bank_mask:0xf bound_ctrl:1
	v_mov_b32_dpp v198, v46 row_ror:8 row_mask:0xf bank_mask:0xf bound_ctrl:1
	v_mov_b32_dpp v199, v47 row_ror:8 row_mask:0xf bank_mask:0xf bound_ctrl:1
	v_pk_mov_b32 v[208:209], v[176:177], v[178:179] op_sel:[0,0]
	v_pk_mov_b32 v[212:213], v[176:177], v[178:179] op_sel:[1,1]
	v_pk_mov_b32 v[210:211], v[180:181], v[182:183] op_sel:[0,0]
	v_pk_mov_b32 v[214:215], v[180:181], v[182:183] op_sel:[1,1]
	v_cndmask_b32_e64 v212, v212, -v212, s[100:101]
	v_cndmask_b32_e64 v213, v213, -v213, s[100:101]
	v_cndmask_b32_e64 v214, v214, -v214, s[100:101]
	v_cndmask_b32_e64 v215, v215, -v215, s[100:101]
	v_pk_mul_f32 v[192:193], v[192:193], v[212:213]
	v_pk_mul_f32 v[194:195], v[194:195], v[214:215]
	v_pk_mul_f32 v[196:197], v[196:197], v[212:213]
	v_pk_mul_f32 v[198:199], v[198:199], v[214:215]
	v_pk_mul_f32 v[36:37], v[36:37], v[208:209]
	v_pk_mul_f32 v[38:39], v[38:39], v[210:211]
	v_pk_mul_f32 v[44:45], v[44:45], v[208:209]
	v_pk_mul_f32 v[46:47], v[46:47], v[210:211]
	v_pk_add_f32 v[36:37], v[36:37], v[192:193]
	v_pk_add_f32 v[38:39], v[38:39], v[194:195]
	v_pk_add_f32 v[44:45], v[44:45], v[196:197]
	v_pk_add_f32 v[46:47], v[46:47], v[198:199]
	v_pk_mul_f32 v[36:37], v[36:37], v[160:161]
	v_pk_mul_f32 v[38:39], v[38:39], v[162:163]
	v_pk_mul_f32 v[44:45], v[44:45], v[160:161]
	v_pk_mul_f32 v[46:47], v[46:47], v[162:163]
	v_pk_mul_f32 v[40:41], v[40:41], v[160:161]
	v_pk_mul_f32 v[42:43], v[42:43], v[162:163]
	v_pk_mul_f32 v[48:49], v[48:49], v[160:161]
	v_pk_mul_f32 v[50:51], v[50:51], v[162:163]
	v_cvt_pk_bf16_f32 v200, v36, v37
	v_cvt_pk_bf16_f32 v201, v38, v39
	v_cvt_pk_bf16_f32 v202, v40, v41
	v_cvt_pk_bf16_f32 v203, v42, v43
	v_cvt_pk_bf16_f32 v204, v44, v45
	v_cvt_pk_bf16_f32 v205, v46, v47
	v_cvt_pk_bf16_f32 v206, v48, v49
	v_cvt_pk_bf16_f32 v207, v50, v51
	v_mov_b32_dpp v208, v200 quad_perm:[1,0,3,2] row_mask:0xf bank_mask:0xf bound_ctrl:1
	v_mov_b32_dpp v209, v201 quad_perm:[1,0,3,2] row_mask:0xf bank_mask:0xf bound_ctrl:1
	v_mov_b32_dpp v210, v202 quad_perm:[1,0,3,2] row_mask:0xf bank_mask:0xf bound_ctrl:1
	v_mov_b32_dpp v211, v203 quad_perm:[1,0,3,2] row_mask:0xf bank_mask:0xf bound_ctrl:1
	v_mov_b32_dpp v212, v204 quad_perm:[1,0,3,2] row_mask:0xf bank_mask:0xf bound_ctrl:1
	v_mov_b32_dpp v213, v205 quad_perm:[1,0,3,2] row_mask:0xf bank_mask:0xf bound_ctrl:1
	v_mov_b32_dpp v214, v206 quad_perm:[1,0,3,2] row_mask:0xf bank_mask:0xf bound_ctrl:1
	v_mov_b32_dpp v215, v207 quad_perm:[1,0,3,2] row_mask:0xf bank_mask:0xf bound_ctrl:1
	v_perm_b32 v200, v208, v200, v190
	v_perm_b32 v201, v209, v201, v190
	v_perm_b32 v202, v210, v202, v190
	v_perm_b32 v203, v211, v203, v190
	v_perm_b32 v204, v212, v204, v190
	v_perm_b32 v205, v213, v205, v190
	v_perm_b32 v206, v214, v206, v190
	v_perm_b32 v207, v215, v207, v190
	global_store_dword v184, v200, s[0:1] offset:1056
	global_store_dword v184, v201, s[4:5] offset:1056
	global_store_dword v184, v202, s[0:1] offset:1184
	global_store_dword v184, v203, s[4:5] offset:1184
	global_store_dword v184, v204, s[6:7] offset:1056
	global_store_dword v184, v205, s[98:99] offset:1056
	global_store_dword v184, v206, s[6:7] offset:1184
	global_store_dword v184, v207, s[98:99] offset:1184
	v_add_u32_e32 v217, 0xb0, v186
	v_and_b32_e32 v217, s8, v217
	v_lshl_or_b32 v217, v217, 6, v188
	global_load_dwordx2 v[176:177], v217, s[42:43]
	v_add_u32_e32 v217, 0xb1, v186
	v_and_b32_e32 v217, s8, v217
	v_lshl_or_b32 v217, v217, 6, v188
	global_load_dwordx2 v[178:179], v217, s[42:43]
	v_add_u32_e32 v217, 0xb2, v186
	v_and_b32_e32 v217, s8, v217
	v_lshl_or_b32 v217, v217, 6, v188
	global_load_dwordx2 v[180:181], v217, s[42:43]
	v_add_u32_e32 v217, 0xb3, v186
	v_and_b32_e32 v217, s8, v217
	v_lshl_or_b32 v217, v217, 6, v188
	global_load_dwordx2 v[182:183], v217, s[42:43]
	v_pk_mul_f32 v[160:161], v[52:53], v[164:165] op_sel_hi:[1,0]
	v_pk_mul_f32 v[162:163], v[54:55], v[164:165] op_sel_hi:[1,0]
	s_waitcnt vmcnt(12)
;   __device__ __forceinline__ void operator()(f32x4 (&acc)[2][2][4][2], int brow, int bcol, int wr, int wc, int fr, int fq) const {
;     ...
;     if (nt < 4) {
;       u16* dst = (u16*)(outb + (nt < 2 ? OUT_QD : OUT_KD));
;       float sc = nt < 2 ? 0.125f * 1.4426950408889634f : 1.f;
;       int cbase = (nt & 1) * 256;
;       const float2* rope = (const float2*)(p.ws + OFF_ROPE);
;       int posmask = brow < NT_P ? 4095 : 8191;
;       bool rot = (wc & 1) == 0;
;       float2 csc[4], csn[4];
; #pragma unroll
;       for (int j = 0; j < 4; ++j) csc[j] = rope[((brow + wr * 64 + fq * 4 + j) & posmask) * 8 + (fr & 7)];
; #pragma unroll
;       for (int ch = 0; ch < 8; ++ch) {
;         const int ai = ch >> 2, m = ch & 3;
;         int row0 = brow + ai * 128 + wr * 64 + m * 16 + fq * 4;
;         if (ch + 1 < 8) {
;           int rown = brow + ((ch + 1) >> 2) * 128 + wr * 64 + ((ch + 1) & 3) * 16 + fq * 4;
; #pragma unroll
;           for (int j = 0; j < 4; ++j) csn[j] = rope[((rown + j) & posmask) * 8 + (fr & 7)];
;         }
;         __builtin_amdgcn_sched_barrier(0);
;         float4 r4 = rsq[ai][m];
;         float rr[4] = {r4.x * sc, r4.y * sc, r4.z * sc, r4.w * sc};
;         float va[2][4], vb[2][4];
; #pragma unroll
;         for (int j = 0; j < 4; ++j) {
;           float2 cs = csc[j];
; #pragma unroll
;           for (int bj = 0; bj < 2; ++bj) {
;             float v = acc[ai][bj][m][0][j];
;             float pr = dpp_f<0x128>(v);
;             float sg = (fr < 8) ? -pr : pr;
;             float vr = v * cs.x + sg * cs.y;
;             v = rot ? vr : v;
;             va[bj][j] = v * rr[j];
;             vb[bj][j] = acc[ai][bj][m][1][j] * rr[j];
;           }
;         }
; #pragma unroll
;         for (int bj = 0; bj < 2; ++bj) {
;           int c = cbase + bj * 128 + wc * 32 + fr;
;           store_rm4(dst, 512, row0, c, va[bj][0], va[bj][1], va[bj][2], va[bj][3], fr & 1);
;           store_rm4(dst, 512, row0, c + 16, vb[bj][0], vb[bj][1], vb[bj][2], vb[bj][3], fr & 1);
;         }
;         __builtin_amdgcn_sched_barrier(0);
; #pragma unroll
;         for (int j = 0; j < 4; ++j) csc[j] = csn[j];
;       }
	v_mov_b32_dpp v192, v16 row_ror:8 row_mask:0xf bank_mask:0xf bound_ctrl:1
	v_mov_b32_dpp v193, v17 row_ror:8 row_mask:0xf bank_mask:0xf bound_ctrl:1
	v_mov_b32_dpp v194, v18 row_ror:8 row_mask:0xf bank_mask:0xf bound_ctrl:1
	v_mov_b32_dpp v195, v19 row_ror:8 row_mask:0xf bank_mask:0xf bound_ctrl:1
	v_mov_b32_dpp v196, v24 row_ror:8 row_mask:0xf bank_mask:0xf bound_ctrl:1
	v_mov_b32_dpp v197, v25 row_ror:8 row_mask:0xf bank_mask:0xf bound_ctrl:1
	v_mov_b32_dpp v198, v26 row_ror:8 row_mask:0xf bank_mask:0xf bound_ctrl:1
	v_mov_b32_dpp v199, v27 row_ror:8 row_mask:0xf bank_mask:0xf bound_ctrl:1
	v_pk_mov_b32 v[208:209], v[168:169], v[170:171] op_sel:[0,0]
	v_pk_mov_b32 v[212:213], v[168:169], v[170:171] op_sel:[1,1]
	v_pk_mov_b32 v[210:211], v[172:173], v[174:175] op_sel:[0,0]
	v_pk_mov_b32 v[214:215], v[172:173], v[174:175] op_sel:[1,1]
	v_cndmask_b32_e64 v212, v212, -v212, s[100:101]
	v_cndmask_b32_e64 v213, v213, -v213, s[100:101]
	v_cndmask_b32_e64 v214, v214, -v214, s[100:101]
	v_cndmask_b32_e64 v215, v215, -v215, s[100:101]
	v_pk_mul_f32 v[192:193], v[192:193], v[212:213]
	v_pk_mul_f32 v[194:195], v[194:195], v[214:215]
	v_pk_mul_f32 v[196:197], v[196:197], v[212:213]
	v_pk_mul_f32 v[198:199], v[198:199], v[214:215]
	v_pk_mul_f32 v[16:17], v[16:17], v[208:209]
	v_pk_mul_f32 v[18:19], v[18:19], v[210:211]
	v_pk_mul_f32 v[24:25], v[24:25], v[208:209]
	v_pk_mul_f32 v[26:27], v[26:27], v[210:211]
	v_pk_add_f32 v[16:17], v[16:17], v[192:193]
	v_pk_add_f32 v[18:19], v[18:19], v[194:195]
	v_pk_add_f32 v[24:25], v[24:25], v[196:197]
	v_pk_add_f32 v[26:27], v[26:27], v[198:199]
	v_pk_mul_f32 v[16:17], v[16:17], v[160:161]
	v_pk_mul_f32 v[18:19], v[18:19], v[162:163]
	v_pk_mul_f32 v[24:25], v[24:25], v[160:161]
	v_pk_mul_f32 v[26:27], v[26:27], v[162:163]
	v_pk_mul_f32 v[20:21], v[20:21], v[160:161]
	v_pk_mul_f32 v[22:23], v[22:23], v[162:163]
	v_pk_mul_f32 v[28:29], v[28:29], v[160:161]
	v_pk_mul_f32 v[30:31], v[30:31], v[162:163]
	v_cvt_pk_bf16_f32 v200, v16, v17
	v_cvt_pk_bf16_f32 v201, v18, v19
	v_cvt_pk_bf16_f32 v202, v20, v21
	v_cvt_pk_bf16_f32 v203, v22, v23
	v_cvt_pk_bf16_f32 v204, v24, v25
	v_cvt_pk_bf16_f32 v205, v26, v27
	v_cvt_pk_bf16_f32 v206, v28, v29
	v_cvt_pk_bf16_f32 v207, v30, v31
	v_mov_b32_dpp v208, v200 quad_perm:[1,0,3,2] row_mask:0xf bank_mask:0xf bound_ctrl:1
	v_mov_b32_dpp v209, v201 quad_perm:[1,0,3,2] row_mask:0xf bank_mask:0xf bound_ctrl:1
	v_mov_b32_dpp v210, v202 quad_perm:[1,0,3,2] row_mask:0xf bank_mask:0xf bound_ctrl:1
	v_mov_b32_dpp v211, v203 quad_perm:[1,0,3,2] row_mask:0xf bank_mask:0xf bound_ctrl:1
	v_mov_b32_dpp v212, v204 quad_perm:[1,0,3,2] row_mask:0xf bank_mask:0xf bound_ctrl:1
	v_mov_b32_dpp v213, v205 quad_perm:[1,0,3,2] row_mask:0xf bank_mask:0xf bound_ctrl:1
	v_mov_b32_dpp v214, v206 quad_perm:[1,0,3,2] row_mask:0xf bank_mask:0xf bound_ctrl:1
	v_mov_b32_dpp v215, v207 quad_perm:[1,0,3,2] row_mask:0xf bank_mask:0xf bound_ctrl:1
	v_perm_b32 v200, v208, v200, v190
	v_perm_b32 v201, v209, v201, v190
	v_perm_b32 v202, v210, v202, v190
	v_perm_b32 v203, v211, v203, v190
	v_perm_b32 v204, v212, v204, v190
	v_perm_b32 v205, v213, v205, v190
	v_perm_b32 v206, v214, v206, v190
	v_perm_b32 v207, v215, v207, v190
	global_store_dword v184, v200, s[0:1] offset:1088
	global_store_dword v184, v201, s[4:5] offset:1088
	global_store_dword v184, v202, s[0:1] offset:1216
	global_store_dword v184, v203, s[4:5] offset:1216
	global_store_dword v184, v204, s[6:7] offset:1088
	global_store_dword v184, v205, s[98:99] offset:1088
	global_store_dword v184, v206, s[6:7] offset:1216
	global_store_dword v184, v207, s[98:99] offset:1216
	v_pk_mul_f32 v[160:161], v[32:33], v[164:165] op_sel_hi:[1,0]
	v_pk_mul_f32 v[162:163], v[34:35], v[164:165] op_sel_hi:[1,0]
	s_waitcnt vmcnt(8)
	v_mov_b32_dpp v192, v0 row_ror:8 row_mask:0xf bank_mask:0xf bound_ctrl:1
	v_mov_b32_dpp v193, v1 row_ror:8 row_mask:0xf bank_mask:0xf bound_ctrl:1
	v_mov_b32_dpp v194, v2 row_ror:8 row_mask:0xf bank_mask:0xf bound_ctrl:1
	v_mov_b32_dpp v195, v3 row_ror:8 row_mask:0xf bank_mask:0xf bound_ctrl:1
	v_mov_b32_dpp v196, v8 row_ror:8 row_mask:0xf bank_mask:0xf bound_ctrl:1
	v_mov_b32_dpp v197, v9 row_ror:8 row_mask:0xf bank_mask:0xf bound_ctrl:1
	v_mov_b32_dpp v198, v10 row_ror:8 row_mask:0xf bank_mask:0xf bound_ctrl:1
	v_mov_b32_dpp v199, v11 row_ror:8 row_mask:0xf bank_mask:0xf bound_ctrl:1
	v_pk_mov_b32 v[208:209], v[176:177], v[178:179] op_sel:[0,0]
	v_pk_mov_b32 v[212:213], v[176:177], v[178:179] op_sel:[1,1]
	v_pk_mov_b32 v[210:211], v[180:181], v[182:183] op_sel:[0,0]
	v_pk_mov_b32 v[214:215], v[180:181], v[182:183] op_sel:[1,1]
	v_cndmask_b32_e64 v212, v212, -v212, s[100:101]
	v_cndmask_b32_e64 v213, v213, -v213, s[100:101]
	v_cndmask_b32_e64 v214, v214, -v214, s[100:101]
	v_cndmask_b32_e64 v215, v215, -v215, s[100:101]
	v_pk_mul_f32 v[192:193], v[192:193], v[212:213]
	v_pk_mul_f32 v[194:195], v[194:195], v[214:215]
	v_pk_mul_f32 v[196:197], v[196:197], v[212:213]
	v_pk_mul_f32 v[198:199], v[198:199], v[214:215]
	v_pk_mul_f32 v[0:1], v[0:1], v[208:209]
	v_pk_mul_f32 v[2:3], v[2:3], v[210:211]
	v_pk_mul_f32 v[8:9], v[8:9], v[208:209]
	v_pk_mul_f32 v[10:11], v[10:11], v[210:211]
	v_pk_add_f32 v[0:1], v[0:1], v[192:193]
	v_pk_add_f32 v[2:3], v[2:3], v[194:195]
	v_pk_add_f32 v[8:9], v[8:9], v[196:197]
	v_pk_add_f32 v[10:11], v[10:11], v[198:199]
	v_pk_mul_f32 v[0:1], v[0:1], v[160:161]
	v_pk_mul_f32 v[2:3], v[2:3], v[162:163]
	v_pk_mul_f32 v[8:9], v[8:9], v[160:161]
	v_pk_mul_f32 v[10:11], v[10:11], v[162:163]
	v_pk_mul_f32 v[4:5], v[4:5], v[160:161]
	v_pk_mul_f32 v[6:7], v[6:7], v[162:163]
	v_pk_mul_f32 v[12:13], v[12:13], v[160:161]
;   __device__ __forceinline__ void operator()(f32x4 (&acc)[2][2][4][2], int brow, int bcol, int wr, int wc, int fr, int fq) const {
;     ...
;     if (nt < 4) {
;       u16* dst = (u16*)(outb + (nt < 2 ? OUT_QD : OUT_KD));
;       float sc = nt < 2 ? 0.125f * 1.4426950408889634f : 1.f;
;       int cbase = (nt & 1) * 256;
;       const float2* rope = (const float2*)(p.ws + OFF_ROPE);
;       int posmask = brow < NT_P ? 4095 : 8191;
;       bool rot = (wc & 1) == 0;
;       float2 csc[4], csn[4];
; #pragma unroll
;       for (int j = 0; j < 4; ++j) csc[j] = rope[((brow + wr * 64 + fq * 4 + j) & posmask) * 8 + (fr & 7)];
; #pragma unroll
;       for (int ch = 0; ch < 8; ++ch) {
;         const int ai = ch >> 2, m = ch & 3;
;         int row0 = brow + ai * 128 + wr * 64 + m * 16 + fq * 4;
;         if (ch + 1 < 8) {
;           int rown = brow + ((ch + 1) >> 2) * 128 + wr * 64 + ((ch + 1) & 3) * 16 + fq * 4;
; #pragma unroll
;           for (int j = 0; j < 4; ++j) csn[j] = rope[((rown + j) & posmask) * 8 + (fr & 7)];
;         }
;         __builtin_amdgcn_sched_barrier(0);
;         float4 r4 = rsq[ai][m];
;         float rr[4] = {r4.x * sc, r4.y * sc, r4.z * sc, r4.w * sc};
;         float va[2][4], vb[2][4];
; #pragma unroll
;         for (int j = 0; j < 4; ++j) {
;           float2 cs = csc[j];
; #pragma unroll
;           for (int bj = 0; bj < 2; ++bj) {
;             float v = acc[ai][bj][m][0][j];
;             float pr = dpp_f<0x128>(v);
;             float sg = (fr < 8) ? -pr : pr;
;             float vr = v * cs.x + sg * cs.y;
;             v = rot ? vr : v;
;             va[bj][j] = v * rr[j];
;             vb[bj][j] = acc[ai][bj][m][1][j] * rr[j];
;           }
;         }
; #pragma unroll
;         for (int bj = 0; bj < 2; ++bj) {
;           int c = cbase + bj * 128 + wc * 32 + fr;
;           store_rm4(dst, 512, row0, c, va[bj][0], va[bj][1], va[bj][2], va[bj][3], fr & 1);
;           store_rm4(dst, 512, row0, c + 16, vb[bj][0], vb[bj][1], vb[bj][2], vb[bj][3], fr & 1);
;         }
;         __builtin_amdgcn_sched_barrier(0);
; #pragma unroll
;         for (int j = 0; j < 4; ++j) csc[j] = csn[j];
;       }
	v_pk_mul_f32 v[14:15], v[14:15], v[162:163]
	v_cvt_pk_bf16_f32 v200, v0, v1
	v_cvt_pk_bf16_f32 v201, v2, v3
	v_cvt_pk_bf16_f32 v202, v4, v5
	v_cvt_pk_bf16_f32 v203, v6, v7
	v_cvt_pk_bf16_f32 v204, v8, v9
	v_cvt_pk_bf16_f32 v205, v10, v11
	v_cvt_pk_bf16_f32 v206, v12, v13
	v_cvt_pk_bf16_f32 v207, v14, v15
	v_mov_b32_dpp v208, v200 quad_perm:[1,0,3,2] row_mask:0xf bank_mask:0xf bound_ctrl:1
	v_mov_b32_dpp v209, v201 quad_perm:[1,0,3,2] row_mask:0xf bank_mask:0xf bound_ctrl:1
	v_mov_b32_dpp v210, v202 quad_perm:[1,0,3,2] row_mask:0xf bank_mask:0xf bound_ctrl:1
	v_mov_b32_dpp v211, v203 quad_perm:[1,0,3,2] row_mask:0xf bank_mask:0xf bound_ctrl:1
	v_mov_b32_dpp v212, v204 quad_perm:[1,0,3,2] row_mask:0xf bank_mask:0xf bound_ctrl:1
	v_mov_b32_dpp v213, v205 quad_perm:[1,0,3,2] row_mask:0xf bank_mask:0xf bound_ctrl:1
	v_mov_b32_dpp v214, v206 quad_perm:[1,0,3,2] row_mask:0xf bank_mask:0xf bound_ctrl:1
	v_mov_b32_dpp v215, v207 quad_perm:[1,0,3,2] row_mask:0xf bank_mask:0xf bound_ctrl:1
	v_perm_b32 v200, v208, v200, v190
	v_perm_b32 v201, v209, v201, v190
	v_perm_b32 v202, v210, v202, v190
	v_perm_b32 v203, v211, v203, v190
	v_perm_b32 v204, v212, v204, v190
	v_perm_b32 v205, v213, v205, v190
	v_perm_b32 v206, v214, v206, v190
	v_perm_b32 v207, v215, v207, v190
	global_store_dword v184, v200, s[0:1] offset:1120
	global_store_dword v184, v201, s[4:5] offset:1120
	global_store_dword v184, v202, s[0:1] offset:1248
	global_store_dword v184, v203, s[4:5] offset:1248
	global_store_dword v184, v204, s[6:7] offset:1120
	global_store_dword v184, v205, s[98:99] offset:1120
	global_store_dword v184, v206, s[6:7] offset:1248
	global_store_dword v184, v207, s[98:99] offset:1248
	s_branch .LBB0_130
.Lmy_rope_norot:
	s_waitcnt vmcnt(0)
	v_pk_mul_f32 v[160:161], v[156:157], v[164:165] op_sel_hi:[1,0]
	v_pk_mul_f32 v[162:163], v[158:159], v[164:165] op_sel_hi:[1,0]
	v_pk_mul_f32 v[136:137], v[136:137], v[160:161]
	v_pk_mul_f32 v[138:139], v[138:139], v[162:163]
	v_pk_mul_f32 v[144:145], v[144:145], v[160:161]
	v_pk_mul_f32 v[146:147], v[146:147], v[162:163]
	v_pk_mul_f32 v[140:141], v[140:141], v[160:161]
	v_pk_mul_f32 v[142:143], v[142:143], v[162:163]
	v_pk_mul_f32 v[148:149], v[148:149], v[160:161]
	v_pk_mul_f32 v[150:151], v[150:151], v[162:163]
	v_cvt_pk_bf16_f32 v200, v136, v137
	v_cvt_pk_bf16_f32 v201, v138, v139
	v_cvt_pk_bf16_f32 v202, v140, v141
	v_cvt_pk_bf16_f32 v203, v142, v143
	v_cvt_pk_bf16_f32 v204, v144, v145
	v_cvt_pk_bf16_f32 v205, v146, v147
	v_cvt_pk_bf16_f32 v206, v148, v149
	v_cvt_pk_bf16_f32 v207, v150, v151
	v_mov_b32_dpp v208, v200 quad_perm:[1,0,3,2] row_mask:0xf bank_mask:0xf bound_ctrl:1
	v_mov_b32_dpp v209, v201 quad_perm:[1,0,3,2] row_mask:0xf bank_mask:0xf bound_ctrl:1
	v_mov_b32_dpp v210, v202 quad_perm:[1,0,3,2] row_mask:0xf bank_mask:0xf bound_ctrl:1
	v_mov_b32_dpp v211, v203 quad_perm:[1,0,3,2] row_mask:0xf bank_mask:0xf bound_ctrl:1
	v_mov_b32_dpp v212, v204 quad_perm:[1,0,3,2] row_mask:0xf bank_mask:0xf bound_ctrl:1
	v_mov_b32_dpp v213, v205 quad_perm:[1,0,3,2] row_mask:0xf bank_mask:0xf bound_ctrl:1
	v_mov_b32_dpp v214, v206 quad_perm:[1,0,3,2] row_mask:0xf bank_mask:0xf bound_ctrl:1
	v_mov_b32_dpp v215, v207 quad_perm:[1,0,3,2] row_mask:0xf bank_mask:0xf bound_ctrl:1
	v_perm_b32 v200, v208, v200, v190
	v_perm_b32 v201, v209, v201, v190
	v_perm_b32 v202, v210, v202, v190
	v_perm_b32 v203, v211, v203, v190
	v_perm_b32 v204, v212, v204, v190
	v_perm_b32 v205, v213, v205, v190
	v_perm_b32 v206, v214, v206, v190
	v_perm_b32 v207, v215, v207, v190
	global_store_dword v184, v200, s[0:1]
	global_store_dword v184, v201, s[4:5]
	global_store_dword v184, v202, s[0:1] offset:128
	global_store_dword v184, v203, s[4:5] offset:128
	global_store_dword v184, v204, s[6:7]
	global_store_dword v184, v205, s[98:99]
	global_store_dword v184, v206, s[6:7] offset:128
	global_store_dword v184, v207, s[98:99] offset:128
	v_pk_mul_f32 v[160:161], v[152:153], v[164:165] op_sel_hi:[1,0]
	v_pk_mul_f32 v[162:163], v[154:155], v[164:165] op_sel_hi:[1,0]
	v_pk_mul_f32 v[116:117], v[116:117], v[160:161]
	v_pk_mul_f32 v[118:119], v[118:119], v[162:163]
	v_pk_mul_f32 v[124:125], v[124:125], v[160:161]
	v_pk_mul_f32 v[126:127], v[126:127], v[162:163]
	v_pk_mul_f32 v[120:121], v[120:121], v[160:161]
	v_pk_mul_f32 v[122:123], v[122:123], v[162:163]
	v_pk_mul_f32 v[128:129], v[128:129], v[160:161]
	v_pk_mul_f32 v[130:131], v[130:131], v[162:163]
	v_cvt_pk_bf16_f32 v200, v116, v117
	v_cvt_pk_bf16_f32 v201, v118, v119
	v_cvt_pk_bf16_f32 v202, v120, v121
	v_cvt_pk_bf16_f32 v203, v122, v123
	v_cvt_pk_bf16_f32 v204, v124, v125
	v_cvt_pk_bf16_f32 v205, v126, v127
	v_cvt_pk_bf16_f32 v206, v128, v129
	v_cvt_pk_bf16_f32 v207, v130, v131
	v_mov_b32_dpp v208, v200 quad_perm:[1,0,3,2] row_mask:0xf bank_mask:0xf bound_ctrl:1
	v_mov_b32_dpp v209, v201 quad_perm:[1,0,3,2] row_mask:0xf bank_mask:0xf bound_ctrl:1
	v_mov_b32_dpp v210, v202 quad_perm:[1,0,3,2] row_mask:0xf bank_mask:0xf bound_ctrl:1
	v_mov_b32_dpp v211, v203 quad_perm:[1,0,3,2] row_mask:0xf bank_mask:0xf bound_ctrl:1
	v_mov_b32_dpp v212, v204 quad_perm:[1,0,3,2] row_mask:0xf bank_mask:0xf bound_ctrl:1
	v_mov_b32_dpp v213, v205 quad_perm:[1,0,3,2] row_mask:0xf bank_mask:0xf bound_ctrl:1
	v_mov_b32_dpp v214, v206 quad_perm:[1,0,3,2] row_mask:0xf bank_mask:0xf bound_ctrl:1
	v_mov_b32_dpp v215, v207 quad_perm:[1,0,3,2] row_mask:0xf bank_mask:0xf bound_ctrl:1
	v_perm_b32 v200, v208, v200, v190
	v_perm_b32 v201, v209, v201, v190
	v_perm_b32 v202, v210, v202, v190
	v_perm_b32 v203, v211, v203, v190
	v_perm_b32 v204, v212, v204, v190
	v_perm_b32 v205, v213, v205, v190
	v_perm_b32 v206, v214, v206, v190
;   __device__ __forceinline__ void operator()(f32x4 (&acc)[2][2][4][2], int brow, int bcol, int wr, int wc, int fr, int fq) const {
;     ...
;         float4 r4 = rsq[ai][m];
;         float rr[4] = {r4.x * sc, r4.y * sc, r4.z * sc, r4.w * sc};
;         float va[2][4], vb[2][4];
; #pragma unroll
;         for (int j = 0; j < 4; ++j) {
;           float2 cs = csc[j];
; #pragma unroll
;           for (int bj = 0; bj < 2; ++bj) {
;             float v = acc[ai][bj][m][0][j];
;             float pr = dpp_f<0x128>(v);
;             float sg = (fr < 8) ? -pr : pr;
;             float vr = v * cs.x + sg * cs.y;
;             v = rot ? vr : v;
;             va[bj][j] = v * rr[j];
;             vb[bj][j] = acc[ai][bj][m][1][j] * rr[j];
;           }
;         }
; #pragma unroll
;         for (int bj = 0; bj < 2; ++bj) {
;           int c = cbase + bj * 128 + wc * 32 + fr;
;           store_rm4(dst, 512, row0, c, va[bj][0], va[bj][1], va[bj][2], va[bj][3], fr & 1);
;           store_rm4(dst, 512, row0, c + 16, vb[bj][0], vb[bj][1], vb[bj][2], vb[bj][3], fr & 1);
;         }
	v_perm_b32 v207, v215, v207, v190
	global_store_dword v184, v200, s[0:1] offset:32
	global_store_dword v184, v201, s[4:5] offset:32
	global_store_dword v184, v202, s[0:1] offset:160
	global_store_dword v184, v203, s[4:5] offset:160
	global_store_dword v184, v204, s[6:7] offset:32
	global_store_dword v184, v205, s[98:99] offset:32
	global_store_dword v184, v206, s[6:7] offset:160
	global_store_dword v184, v207, s[98:99] offset:160
	v_pk_mul_f32 v[160:161], v[132:133], v[164:165] op_sel_hi:[1,0]
	v_pk_mul_f32 v[162:163], v[134:135], v[164:165] op_sel_hi:[1,0]
	v_pk_mul_f32 v[96:97], v[96:97], v[160:161]
	v_pk_mul_f32 v[98:99], v[98:99], v[162:163]
	v_pk_mul_f32 v[104:105], v[104:105], v[160:161]
	v_pk_mul_f32 v[106:107], v[106:107], v[162:163]
	v_pk_mul_f32 v[100:101], v[100:101], v[160:161]
	v_pk_mul_f32 v[102:103], v[102:103], v[162:163]
	v_pk_mul_f32 v[108:109], v[108:109], v[160:161]
	v_pk_mul_f32 v[110:111], v[110:111], v[162:163]
	v_cvt_pk_bf16_f32 v200, v96, v97
	v_cvt_pk_bf16_f32 v201, v98, v99
	v_cvt_pk_bf16_f32 v202, v100, v101
	v_cvt_pk_bf16_f32 v203, v102, v103
	v_cvt_pk_bf16_f32 v204, v104, v105
	v_cvt_pk_bf16_f32 v205, v106, v107
	v_cvt_pk_bf16_f32 v206, v108, v109
	v_cvt_pk_bf16_f32 v207, v110, v111
	v_mov_b32_dpp v208, v200 quad_perm:[1,0,3,2] row_mask:0xf bank_mask:0xf bound_ctrl:1
	v_mov_b32_dpp v209, v201 quad_perm:[1,0,3,2] row_mask:0xf bank_mask:0xf bound_ctrl:1
	v_mov_b32_dpp v210, v202 quad_perm:[1,0,3,2] row_mask:0xf bank_mask:0xf bound_ctrl:1
	v_mov_b32_dpp v211, v203 quad_perm:[1,0,3,2] row_mask:0xf bank_mask:0xf bound_ctrl:1
	v_mov_b32_dpp v212, v204 quad_perm:[1,0,3,2] row_mask:0xf bank_mask:0xf bound_ctrl:1
	v_mov_b32_dpp v213, v205 quad_perm:[1,0,3,2] row_mask:0xf bank_mask:0xf bound_ctrl:1
	v_mov_b32_dpp v214, v206 quad_perm:[1,0,3,2] row_mask:0xf bank_mask:0xf bound_ctrl:1
	v_mov_b32_dpp v215, v207 quad_perm:[1,0,3,2] row_mask:0xf bank_mask:0xf bound_ctrl:1
	v_perm_b32 v200, v208, v200, v190
	v_perm_b32 v201, v209, v201, v190
	v_perm_b32 v202, v210, v202, v190
	v_perm_b32 v203, v211, v203, v190
	v_perm_b32 v204, v212, v204, v190
	v_perm_b32 v205, v213, v205, v190
	v_perm_b32 v206, v214, v206, v190
	v_perm_b32 v207, v215, v207, v190
	global_store_dword v184, v200, s[0:1] offset:64
	global_store_dword v184, v201, s[4:5] offset:64
	global_store_dword v184, v202, s[0:1] offset:192
	global_store_dword v184, v203, s[4:5] offset:192
	global_store_dword v184, v204, s[6:7] offset:64
	global_store_dword v184, v205, s[98:99] offset:64
	global_store_dword v184, v206, s[6:7] offset:192
	global_store_dword v184, v207, s[98:99] offset:192
	v_pk_mul_f32 v[160:161], v[112:113], v[164:165] op_sel_hi:[1,0]
	v_pk_mul_f32 v[162:163], v[114:115], v[164:165] op_sel_hi:[1,0]
	v_pk_mul_f32 v[76:77], v[76:77], v[160:161]
	v_pk_mul_f32 v[78:79], v[78:79], v[162:163]
	v_pk_mul_f32 v[84:85], v[84:85], v[160:161]
	v_pk_mul_f32 v[86:87], v[86:87], v[162:163]
	v_pk_mul_f32 v[80:81], v[80:81], v[160:161]
	v_pk_mul_f32 v[82:83], v[82:83], v[162:163]
	v_pk_mul_f32 v[88:89], v[88:89], v[160:161]
	v_pk_mul_f32 v[90:91], v[90:91], v[162:163]
	v_cvt_pk_bf16_f32 v200, v76, v77
	v_cvt_pk_bf16_f32 v201, v78, v79
	v_cvt_pk_bf16_f32 v202, v80, v81
	v_cvt_pk_bf16_f32 v203, v82, v83
	v_cvt_pk_bf16_f32 v204, v84, v85
	v_cvt_pk_bf16_f32 v205, v86, v87
	v_cvt_pk_bf16_f32 v206, v88, v89
	v_cvt_pk_bf16_f32 v207, v90, v91
	v_mov_b32_dpp v208, v200 quad_perm:[1,0,3,2] row_mask:0xf bank_mask:0xf bound_ctrl:1
	v_mov_b32_dpp v209, v201 quad_perm:[1,0,3,2] row_mask:0xf bank_mask:0xf bound_ctrl:1
	v_mov_b32_dpp v210, v202 quad_perm:[1,0,3,2] row_mask:0xf bank_mask:0xf bound_ctrl:1
	v_mov_b32_dpp v211, v203 quad_perm:[1,0,3,2] row_mask:0xf bank_mask:0xf bound_ctrl:1
	v_mov_b32_dpp v212, v204 quad_perm:[1,0,3,2] row_mask:0xf bank_mask:0xf bound_ctrl:1
	v_mov_b32_dpp v213, v205 quad_perm:[1,0,3,2] row_mask:0xf bank_mask:0xf bound_ctrl:1
	v_mov_b32_dpp v214, v206 quad_perm:[1,0,3,2] row_mask:0xf bank_mask:0xf bound_ctrl:1
	v_mov_b32_dpp v215, v207 quad_perm:[1,0,3,2] row_mask:0xf bank_mask:0xf bound_ctrl:1
	v_perm_b32 v200, v208, v200, v190
	v_perm_b32 v201, v209, v201, v190
	v_perm_b32 v202, v210, v202, v190
	v_perm_b32 v203, v211, v203, v190
	v_perm_b32 v204, v212, v204, v190
	v_perm_b32 v205, v213, v205, v190
	v_perm_b32 v206, v214, v206, v190
	v_perm_b32 v207, v215, v207, v190
	global_store_dword v184, v200, s[0:1] offset:96
	global_store_dword v184, v201, s[4:5] offset:96
	global_store_dword v184, v202, s[0:1] offset:224
	global_store_dword v184, v203, s[4:5] offset:224
	global_store_dword v184, v204, s[6:7] offset:96
	global_store_dword v184, v205, s[98:99] offset:96
	global_store_dword v184, v206, s[6:7] offset:224
	global_store_dword v184, v207, s[98:99] offset:224
	v_pk_mul_f32 v[160:161], v[92:93], v[164:165] op_sel_hi:[1,0]
	v_pk_mul_f32 v[162:163], v[94:95], v[164:165] op_sel_hi:[1,0]
	v_pk_mul_f32 v[56:57], v[56:57], v[160:161]
	v_pk_mul_f32 v[58:59], v[58:59], v[162:163]
	v_pk_mul_f32 v[64:65], v[64:65], v[160:161]
	v_pk_mul_f32 v[66:67], v[66:67], v[162:163]
	v_pk_mul_f32 v[60:61], v[60:61], v[160:161]
	v_pk_mul_f32 v[62:63], v[62:63], v[162:163]
	v_pk_mul_f32 v[68:69], v[68:69], v[160:161]
	v_pk_mul_f32 v[70:71], v[70:71], v[162:163]
	v_cvt_pk_bf16_f32 v200, v56, v57
	v_cvt_pk_bf16_f32 v201, v58, v59
	v_cvt_pk_bf16_f32 v202, v60, v61
	v_cvt_pk_bf16_f32 v203, v62, v63
	v_cvt_pk_bf16_f32 v204, v64, v65
	v_cvt_pk_bf16_f32 v205, v66, v67
	v_cvt_pk_bf16_f32 v206, v68, v69
	v_cvt_pk_bf16_f32 v207, v70, v71
	v_mov_b32_dpp v208, v200 quad_perm:[1,0,3,2] row_mask:0xf bank_mask:0xf bound_ctrl:1
	v_mov_b32_dpp v209, v201 quad_perm:[1,0,3,2] row_mask:0xf bank_mask:0xf bound_ctrl:1
;   __device__ __forceinline__ void operator()(f32x4 (&acc)[2][2][4][2], int brow, int bcol, int wr, int wc, int fr, int fq) const {
;     ...
;         float4 r4 = rsq[ai][m];
;         float rr[4] = {r4.x * sc, r4.y * sc, r4.z * sc, r4.w * sc};
;         float va[2][4], vb[2][4];
; #pragma unroll
;         for (int j = 0; j < 4; ++j) {
;           float2 cs = csc[j];
; #pragma unroll
;           for (int bj = 0; bj < 2; ++bj) {
;             float v = acc[ai][bj][m][0][j];
;             float pr = dpp_f<0x128>(v);
;             float sg = (fr < 8) ? -pr : pr;
;             float vr = v * cs.x + sg * cs.y;
;             v = rot ? vr : v;
;             va[bj][j] = v * rr[j];
;             vb[bj][j] = acc[ai][bj][m][1][j] * rr[j];
;           }
;         }
; #pragma unroll
;         for (int bj = 0; bj < 2; ++bj) {
;           int c = cbase + bj * 128 + wc * 32 + fr;
;           store_rm4(dst, 512, row0, c, va[bj][0], va[bj][1], va[bj][2], va[bj][3], fr & 1);
;           store_rm4(dst, 512, row0, c + 16, vb[bj][0], vb[bj][1], vb[bj][2], vb[bj][3], fr & 1);
;         }
	v_mov_b32_dpp v210, v202 quad_perm:[1,0,3,2] row_mask:0xf bank_mask:0xf bound_ctrl:1
	v_mov_b32_dpp v211, v203 quad_perm:[1,0,3,2] row_mask:0xf bank_mask:0xf bound_ctrl:1
	v_mov_b32_dpp v212, v204 quad_perm:[1,0,3,2] row_mask:0xf bank_mask:0xf bound_ctrl:1
	v_mov_b32_dpp v213, v205 quad_perm:[1,0,3,2] row_mask:0xf bank_mask:0xf bound_ctrl:1
	v_mov_b32_dpp v214, v206 quad_perm:[1,0,3,2] row_mask:0xf bank_mask:0xf bound_ctrl:1
	v_mov_b32_dpp v215, v207 quad_perm:[1,0,3,2] row_mask:0xf bank_mask:0xf bound_ctrl:1
	v_perm_b32 v200, v208, v200, v190
	v_perm_b32 v201, v209, v201, v190
	v_perm_b32 v202, v210, v202, v190
	v_perm_b32 v203, v211, v203, v190
	v_perm_b32 v204, v212, v204, v190
	v_perm_b32 v205, v213, v205, v190
	v_perm_b32 v206, v214, v206, v190
	v_perm_b32 v207, v215, v207, v190
	global_store_dword v184, v200, s[0:1] offset:1024
	global_store_dword v184, v201, s[4:5] offset:1024
	global_store_dword v184, v202, s[0:1] offset:1152
	global_store_dword v184, v203, s[4:5] offset:1152
	global_store_dword v184, v204, s[6:7] offset:1024
	global_store_dword v184, v205, s[98:99] offset:1024
	global_store_dword v184, v206, s[6:7] offset:1152
	global_store_dword v184, v207, s[98:99] offset:1152
	v_pk_mul_f32 v[160:161], v[72:73], v[164:165] op_sel_hi:[1,0]
	v_pk_mul_f32 v[162:163], v[74:75], v[164:165] op_sel_hi:[1,0]
	v_pk_mul_f32 v[36:37], v[36:37], v[160:161]
	v_pk_mul_f32 v[38:39], v[38:39], v[162:163]
	v_pk_mul_f32 v[44:45], v[44:45], v[160:161]
	v_pk_mul_f32 v[46:47], v[46:47], v[162:163]
	v_pk_mul_f32 v[40:41], v[40:41], v[160:161]
	v_pk_mul_f32 v[42:43], v[42:43], v[162:163]
	v_pk_mul_f32 v[48:49], v[48:49], v[160:161]
	v_pk_mul_f32 v[50:51], v[50:51], v[162:163]
	v_cvt_pk_bf16_f32 v200, v36, v37
	v_cvt_pk_bf16_f32 v201, v38, v39
	v_cvt_pk_bf16_f32 v202, v40, v41
	v_cvt_pk_bf16_f32 v203, v42, v43
	v_cvt_pk_bf16_f32 v204, v44, v45
	v_cvt_pk_bf16_f32 v205, v46, v47
	v_cvt_pk_bf16_f32 v206, v48, v49
	v_cvt_pk_bf16_f32 v207, v50, v51
	v_mov_b32_dpp v208, v200 quad_perm:[1,0,3,2] row_mask:0xf bank_mask:0xf bound_ctrl:1
	v_mov_b32_dpp v209, v201 quad_perm:[1,0,3,2] row_mask:0xf bank_mask:0xf bound_ctrl:1
	v_mov_b32_dpp v210, v202 quad_perm:[1,0,3,2] row_mask:0xf bank_mask:0xf bound_ctrl:1
	v_mov_b32_dpp v211, v203 quad_perm:[1,0,3,2] row_mask:0xf bank_mask:0xf bound_ctrl:1
	v_mov_b32_dpp v212, v204 quad_perm:[1,0,3,2] row_mask:0xf bank_mask:0xf bound_ctrl:1
	v_mov_b32_dpp v213, v205 quad_perm:[1,0,3,2] row_mask:0xf bank_mask:0xf bound_ctrl:1
	v_mov_b32_dpp v214, v206 quad_perm:[1,0,3,2] row_mask:0xf bank_mask:0xf bound_ctrl:1
	v_mov_b32_dpp v215, v207 quad_perm:[1,0,3,2] row_mask:0xf bank_mask:0xf bound_ctrl:1
	v_perm_b32 v200, v208, v200, v190
	v_perm_b32 v201, v209, v201, v190
	v_perm_b32 v202, v210, v202, v190
	v_perm_b32 v203, v211, v203, v190
	v_perm_b32 v204, v212, v204, v190
	v_perm_b32 v205, v213, v205, v190
	v_perm_b32 v206, v214, v206, v190
	v_perm_b32 v207, v215, v207, v190
	global_store_dword v184, v200, s[0:1] offset:1056
	global_store_dword v184, v201, s[4:5] offset:1056
	global_store_dword v184, v202, s[0:1] offset:1184
	global_store_dword v184, v203, s[4:5] offset:1184
	global_store_dword v184, v204, s[6:7] offset:1056
	global_store_dword v184, v205, s[98:99] offset:1056
	global_store_dword v184, v206, s[6:7] offset:1184
	global_store_dword v184, v207, s[98:99] offset:1184
	v_pk_mul_f32 v[160:161], v[52:53], v[164:165] op_sel_hi:[1,0]
	v_pk_mul_f32 v[162:163], v[54:55], v[164:165] op_sel_hi:[1,0]
	v_pk_mul_f32 v[16:17], v[16:17], v[160:161]
	v_pk_mul_f32 v[18:19], v[18:19], v[162:163]
	v_pk_mul_f32 v[24:25], v[24:25], v[160:161]
	v_pk_mul_f32 v[26:27], v[26:27], v[162:163]
	v_pk_mul_f32 v[20:21], v[20:21], v[160:161]
	v_pk_mul_f32 v[22:23], v[22:23], v[162:163]
	v_pk_mul_f32 v[28:29], v[28:29], v[160:161]
;   __device__ __forceinline__ void operator()(f32x4 (&acc)[2][2][4][2], int brow, int bcol, int wr, int wc, int fr, int fq) const {
;     ...
;         float4 r4 = rsq[ai][m];
;         float rr[4] = {r4.x * sc, r4.y * sc, r4.z * sc, r4.w * sc};
;         float va[2][4], vb[2][4];
; #pragma unroll
;         for (int j = 0; j < 4; ++j) {
;           float2 cs = csc[j];
; #pragma unroll
;           for (int bj = 0; bj < 2; ++bj) {
;             float v = acc[ai][bj][m][0][j];
;             float pr = dpp_f<0x128>(v);
;             float sg = (fr < 8) ? -pr : pr;
;             float vr = v * cs.x + sg * cs.y;
;             v = rot ? vr : v;
;             va[bj][j] = v * rr[j];
;             vb[bj][j] = acc[ai][bj][m][1][j] * rr[j];
;           }
;         }
; #pragma unroll
;         for (int bj = 0; bj < 2; ++bj) {
;           int c = cbase + bj * 128 + wc * 32 + fr;
;           store_rm4(dst, 512, row0, c, va[bj][0], va[bj][1], va[bj][2], va[bj][3], fr & 1);
;           store_rm4(dst, 512, row0, c + 16, vb[bj][0], vb[bj][1], vb[bj][2], vb[bj][3], fr & 1);
;         }
	v_pk_mul_f32 v[30:31], v[30:31], v[162:163]
	v_cvt_pk_bf16_f32 v200, v16, v17
	v_cvt_pk_bf16_f32 v201, v18, v19
	v_cvt_pk_bf16_f32 v202, v20, v21
	v_cvt_pk_bf16_f32 v203, v22, v23
	v_cvt_pk_bf16_f32 v204, v24, v25
	v_cvt_pk_bf16_f32 v205, v26, v27
	v_cvt_pk_bf16_f32 v206, v28, v29
	v_cvt_pk_bf16_f32 v207, v30, v31
	v_mov_b32_dpp v208, v200 quad_perm:[1,0,3,2] row_mask:0xf bank_mask:0xf bound_ctrl:1
	v_mov_b32_dpp v209, v201 quad_perm:[1,0,3,2] row_mask:0xf bank_mask:0xf bound_ctrl:1
	v_mov_b32_dpp v210, v202 quad_perm:[1,0,3,2] row_mask:0xf bank_mask:0xf bound_ctrl:1
	v_mov_b32_dpp v211, v203 quad_perm:[1,0,3,2] row_mask:0xf bank_mask:0xf bound_ctrl:1
	v_mov_b32_dpp v212, v204 quad_perm:[1,0,3,2] row_mask:0xf bank_mask:0xf bound_ctrl:1
	v_mov_b32_dpp v213, v205 quad_perm:[1,0,3,2] row_mask:0xf bank_mask:0xf bound_ctrl:1
	v_mov_b32_dpp v214, v206 quad_perm:[1,0,3,2] row_mask:0xf bank_mask:0xf bound_ctrl:1
	v_mov_b32_dpp v215, v207 quad_perm:[1,0,3,2] row_mask:0xf bank_mask:0xf bound_ctrl:1
	v_perm_b32 v200, v208, v200, v190
	v_perm_b32 v201, v209, v201, v190
	v_perm_b32 v202, v210, v202, v190
	v_perm_b32 v203, v211, v203, v190
	v_perm_b32 v204, v212, v204, v190
	v_perm_b32 v205, v213, v205, v190
	v_perm_b32 v206, v214, v206, v190
	v_perm_b32 v207, v215, v207, v190
	global_store_dword v184, v200, s[0:1] offset:1088
	global_store_dword v184, v201, s[4:5] offset:1088
	global_store_dword v184, v202, s[0:1] offset:1216
	global_store_dword v184, v203, s[4:5] offset:1216
	global_store_dword v184, v204, s[6:7] offset:1088
	global_store_dword v184, v205, s[98:99] offset:1088
	global_store_dword v184, v206, s[6:7] offset:1216
	global_store_dword v184, v207, s[98:99] offset:1216
	v_pk_mul_f32 v[160:161], v[32:33], v[164:165] op_sel_hi:[1,0]
	v_pk_mul_f32 v[162:163], v[34:35], v[164:165] op_sel_hi:[1,0]
	v_pk_mul_f32 v[0:1], v[0:1], v[160:161]
	v_pk_mul_f32 v[2:3], v[2:3], v[162:163]
	v_pk_mul_f32 v[8:9], v[8:9], v[160:161]
	v_pk_mul_f32 v[10:11], v[10:11], v[162:163]
	v_pk_mul_f32 v[4:5], v[4:5], v[160:161]
	v_pk_mul_f32 v[6:7], v[6:7], v[162:163]
	v_pk_mul_f32 v[12:13], v[12:13], v[160:161]
	v_pk_mul_f32 v[14:15], v[14:15], v[162:163]
	v_cvt_pk_bf16_f32 v200, v0, v1
	v_cvt_pk_bf16_f32 v201, v2, v3
	v_cvt_pk_bf16_f32 v202, v4, v5
	v_cvt_pk_bf16_f32 v203, v6, v7
	v_cvt_pk_bf16_f32 v204, v8, v9
	v_cvt_pk_bf16_f32 v205, v10, v11
	v_cvt_pk_bf16_f32 v206, v12, v13
	v_cvt_pk_bf16_f32 v207, v14, v15
	v_mov_b32_dpp v208, v200 quad_perm:[1,0,3,2] row_mask:0xf bank_mask:0xf bound_ctrl:1
	v_mov_b32_dpp v209, v201 quad_perm:[1,0,3,2] row_mask:0xf bank_mask:0xf bound_ctrl:1
	v_mov_b32_dpp v210, v202 quad_perm:[1,0,3,2] row_mask:0xf bank_mask:0xf bound_ctrl:1
	v_mov_b32_dpp v211, v203 quad_perm:[1,0,3,2] row_mask:0xf bank_mask:0xf bound_ctrl:1
	v_mov_b32_dpp v212, v204 quad_perm:[1,0,3,2] row_mask:0xf bank_mask:0xf bound_ctrl:1
	v_mov_b32_dpp v213, v205 quad_perm:[1,0,3,2] row_mask:0xf bank_mask:0xf bound_ctrl:1
	v_mov_b32_dpp v214, v206 quad_perm:[1,0,3,2] row_mask:0xf bank_mask:0xf bound_ctrl:1
	v_mov_b32_dpp v215, v207 quad_perm:[1,0,3,2] row_mask:0xf bank_mask:0xf bound_ctrl:1
	v_perm_b32 v200, v208, v200, v190
	v_perm_b32 v201, v209, v201, v190
	v_perm_b32 v202, v210, v202, v190
	v_perm_b32 v203, v211, v203, v190
	v_perm_b32 v204, v212, v204, v190
	v_perm_b32 v205, v213, v205, v190
	v_perm_b32 v206, v214, v206, v190
	v_perm_b32 v207, v215, v207, v190
	global_store_dword v184, v200, s[0:1] offset:1120
	global_store_dword v184, v201, s[4:5] offset:1120
	global_store_dword v184, v202, s[0:1] offset:1248
	global_store_dword v184, v203, s[4:5] offset:1248
	global_store_dword v184, v204, s[6:7] offset:1120
	global_store_dword v184, v205, s[98:99] offset:1120
	global_store_dword v184, v206, s[6:7] offset:1248
	global_store_dword v184, v207, s[98:99] offset:1248
	s_branch .LBB0_130
